# GEMM K-loops: barrier after the step's last MFMA group with late A DMAs (B gets one more group of lead)
# baseline (speedup 1.0000x reference)
.Lg161_loop:
	s_add_u32 s51, s50, 0x10000
	s_sub_u32 s53, s51, 0x28000
	s_cmp_ge_u32 s51, 0x28000
	s_cselect_b32 s51, s53, s51
	s_add_u32 s52, s49, 0x20000
	s_sub_u32 s53, s52, 0x28000
	s_cmp_ge_u32 s52, 0x28000
	s_cselect_b32 s52, s53, s52
	v_add_u32_e32 v137, s50, v135
	s_waitcnt lgkmcnt(4)
	s_waitcnt lgkmcnt(3)
	v_mfma_f32_16x16x32_bf16 v[112:115], v[164:167], v[224:227], v[112:115]
	v_mfma_f32_16x16x32_bf16 v[120:123], v[168:171], v[224:227], v[120:123]
	v_mfma_f32_16x16x32_bf16 v[96:99], v[172:175], v[224:227], v[96:99]
	v_mfma_f32_16x16x32_bf16 v[104:107], v[176:179], v[224:227], v[104:107]
	s_add_u32 m0, s51, s48
	s_nop 0
	global_load_lds_dwordx4 v139, s[64:65]
	s_add_u32 s64, s64, 0x80
	s_addc_u32 s65, s65, 0
	s_add_u32 s53, s51, s48
	s_add_u32 m0, s53, 0x2000
	s_nop 0
	global_load_lds_dwordx4 v139, s[66:67]
	s_add_u32 s66, s66, 0x80
	s_addc_u32 s67, s67, 0
	ds_read_b128 v[224:227], v136 offset:8192
	ds_read_b128 v[180:183], v137
	s_waitcnt lgkmcnt(4)
	v_mfma_f32_16x16x32_bf16 v[116:119], v[164:167], v[228:231], v[116:119]
	v_mfma_f32_16x16x32_bf16 v[124:127], v[168:171], v[228:231], v[124:127]
	v_mfma_f32_16x16x32_bf16 v[100:103], v[172:175], v[228:231], v[100:103]
	v_mfma_f32_16x16x32_bf16 v[108:111], v[176:179], v[228:231], v[108:111]
	s_add_u32 s53, s51, s48
	s_add_u32 m0, s53, 0x4000
	s_nop 0
	global_load_lds_dwordx4 v139, s[68:69]
	s_add_u32 s68, s68, 0x80
	s_addc_u32 s69, s69, 0
	s_add_u32 s53, s51, s48
	s_add_u32 m0, s53, 0x6000
	s_nop 0
	global_load_lds_dwordx4 v139, s[70:71]
	s_add_u32 s70, s70, 0x80
	s_addc_u32 s71, s71, 0
	ds_read_b128 v[228:231], v136 offset:10240
	ds_read_b128 v[212:215], v137 offset:2048
	s_waitcnt lgkmcnt(5)
	v_mfma_f32_16x16x32_bf16 v[80:83], v[164:167], v[232:235], v[80:83]
	v_mfma_f32_16x16x32_bf16 v[88:91], v[168:171], v[232:235], v[88:91]
	v_mfma_f32_16x16x32_bf16 v[64:67], v[172:175], v[232:235], v[64:67]
	v_mfma_f32_16x16x32_bf16 v[72:75], v[176:179], v[232:235], v[72:75]
	ds_read_b128 v[232:235], v136 offset:12288
	ds_read_b128 v[216:219], v137 offset:4096
	s_waitcnt lgkmcnt(6)
	v_mfma_f32_16x16x32_bf16 v[84:87], v[164:167], v[236:239], v[84:87]
	v_mfma_f32_16x16x32_bf16 v[92:95], v[168:171], v[236:239], v[92:95]
	v_mfma_f32_16x16x32_bf16 v[68:71], v[172:175], v[236:239], v[68:71]
	v_mfma_f32_16x16x32_bf16 v[76:79], v[176:179], v[236:239], v[76:79]
	ds_read_b128 v[236:239], v136 offset:14336
	ds_read_b128 v[220:223], v137 offset:6144
	v_add_u32_e32 v136, s49, v133
	s_waitcnt lgkmcnt(7)
	v_mfma_f32_16x16x32_bf16 v[48:51], v[164:167], v[224:227], v[48:51]
	v_mfma_f32_16x16x32_bf16 v[56:59], v[168:171], v[224:227], v[56:59]
	v_mfma_f32_16x16x32_bf16 v[32:35], v[172:175], v[224:227], v[32:35]
	v_mfma_f32_16x16x32_bf16 v[40:43], v[176:179], v[224:227], v[40:43]
	ds_read_b128 v[224:227], v136
	s_waitcnt lgkmcnt(6)
	v_mfma_f32_16x16x32_bf16 v[52:55], v[164:167], v[228:231], v[52:55]
	v_mfma_f32_16x16x32_bf16 v[60:63], v[168:171], v[228:231], v[60:63]
	v_mfma_f32_16x16x32_bf16 v[36:39], v[172:175], v[228:231], v[36:39]
	v_mfma_f32_16x16x32_bf16 v[44:47], v[176:179], v[228:231], v[44:47]
	ds_read_b128 v[228:231], v136 offset:2048
	s_waitcnt lgkmcnt(5)
	v_mfma_f32_16x16x32_bf16 v[16:19], v[164:167], v[232:235], v[16:19]
	v_mfma_f32_16x16x32_bf16 v[24:27], v[168:171], v[232:235], v[24:27]
	v_mfma_f32_16x16x32_bf16 v[0:3], v[172:175], v[232:235], v[0:3]
	v_mfma_f32_16x16x32_bf16 v[8:11], v[176:179], v[232:235], v[8:11]
	ds_read_b128 v[232:235], v136 offset:4096
	s_waitcnt lgkmcnt(4)
	v_mfma_f32_16x16x32_bf16 v[20:23], v[164:167], v[236:239], v[20:23]
	v_mfma_f32_16x16x32_bf16 v[28:31], v[168:171], v[236:239], v[28:31]
	v_mfma_f32_16x16x32_bf16 v[4:7], v[172:175], v[236:239], v[4:7]
	v_mfma_f32_16x16x32_bf16 v[12:15], v[176:179], v[236:239], v[12:15]
	ds_read_b128 v[236:239], v136 offset:6144
	s_waitcnt lgkmcnt(4)
	s_waitcnt lgkmcnt(3)
	v_mfma_f32_16x16x32_bf16 v[112:115], v[180:183], v[224:227], v[112:115]
	v_mfma_f32_16x16x32_bf16 v[120:123], v[212:215], v[224:227], v[120:123]
	v_mfma_f32_16x16x32_bf16 v[96:99], v[216:219], v[224:227], v[96:99]
	v_mfma_f32_16x16x32_bf16 v[104:107], v[220:223], v[224:227], v[104:107]
	ds_read_b128 v[224:227], v136 offset:8192
	s_waitcnt lgkmcnt(3)
	v_mfma_f32_16x16x32_bf16 v[116:119], v[180:183], v[228:231], v[116:119]
	v_mfma_f32_16x16x32_bf16 v[124:127], v[212:215], v[228:231], v[124:127]
	v_mfma_f32_16x16x32_bf16 v[100:103], v[216:219], v[228:231], v[100:103]
	v_mfma_f32_16x16x32_bf16 v[108:111], v[220:223], v[228:231], v[108:111]
	ds_read_b128 v[228:231], v136 offset:10240
	s_waitcnt lgkmcnt(3)
	v_mfma_f32_16x16x32_bf16 v[80:83], v[180:183], v[232:235], v[80:83]
	v_mfma_f32_16x16x32_bf16 v[88:91], v[212:215], v[232:235], v[88:91]
	v_mfma_f32_16x16x32_bf16 v[64:67], v[216:219], v[232:235], v[64:67]
	v_mfma_f32_16x16x32_bf16 v[72:75], v[220:223], v[232:235], v[72:75]
	ds_read_b128 v[232:235], v136 offset:12288
	s_waitcnt lgkmcnt(3)
	v_mfma_f32_16x16x32_bf16 v[84:87], v[180:183], v[236:239], v[84:87]
	v_mfma_f32_16x16x32_bf16 v[92:95], v[212:215], v[236:239], v[92:95]
	v_mfma_f32_16x16x32_bf16 v[68:71], v[216:219], v[236:239], v[68:71]
	v_mfma_f32_16x16x32_bf16 v[76:79], v[220:223], v[236:239], v[76:79]
	ds_read_b128 v[236:239], v136 offset:14336
	s_waitcnt lgkmcnt(3)
	v_mfma_f32_16x16x32_bf16 v[48:51], v[180:183], v[224:227], v[48:51]
	v_mfma_f32_16x16x32_bf16 v[56:59], v[212:215], v[224:227], v[56:59]
	v_mfma_f32_16x16x32_bf16 v[32:35], v[216:219], v[224:227], v[32:35]
	v_mfma_f32_16x16x32_bf16 v[40:43], v[220:223], v[224:227], v[40:43]
	s_add_u32 m0, s52, s48
	s_nop 0
	global_load_lds_dwordx4 v138, s[56:57]
	s_add_u32 s56, s56, 0x80
	s_addc_u32 s57, s57, 0
	s_add_u32 s53, s52, s48
	s_add_u32 m0, s53, 0x2000
	s_nop 0
	global_load_lds_dwordx4 v138, s[58:59]
	s_add_u32 s58, s58, 0x80
	s_addc_u32 s59, s59, 0
	s_waitcnt lgkmcnt(2)
	v_mfma_f32_16x16x32_bf16 v[52:55], v[180:183], v[228:231], v[52:55]
	v_mfma_f32_16x16x32_bf16 v[60:63], v[212:215], v[228:231], v[60:63]
	v_mfma_f32_16x16x32_bf16 v[36:39], v[216:219], v[228:231], v[36:39]
	v_mfma_f32_16x16x32_bf16 v[44:47], v[220:223], v[228:231], v[44:47]
	s_add_u32 s53, s52, s48
	s_add_u32 m0, s53, 0x4000
	s_nop 0
	global_load_lds_dwordx4 v138, s[60:61]
	s_add_u32 s60, s60, 0x80
	s_addc_u32 s61, s61, 0
	s_add_u32 s53, s52, s48
	s_add_u32 m0, s53, 0x6000
	s_nop 0
	global_load_lds_dwordx4 v138, s[62:63]
	s_add_u32 s62, s62, 0x80
	s_addc_u32 s63, s63, 0
	s_waitcnt lgkmcnt(1)
	v_mfma_f32_16x16x32_bf16 v[16:19], v[180:183], v[232:235], v[16:19]
	v_mfma_f32_16x16x32_bf16 v[24:27], v[212:215], v[232:235], v[24:27]
	v_mfma_f32_16x16x32_bf16 v[0:3], v[216:219], v[232:235], v[0:3]
	v_mfma_f32_16x16x32_bf16 v[8:11], v[220:223], v[232:235], v[8:11]
	s_waitcnt lgkmcnt(0)
	v_mfma_f32_16x16x32_bf16 v[20:23], v[180:183], v[236:239], v[20:23]
	v_mfma_f32_16x16x32_bf16 v[28:31], v[212:215], v[236:239], v[28:31]
	v_mfma_f32_16x16x32_bf16 v[4:7], v[216:219], v[236:239], v[4:7]
	v_mfma_f32_16x16x32_bf16 v[12:15], v[220:223], v[236:239], v[12:15]
	s_waitcnt lgkmcnt(0)
	s_add_u32 s4, s4, 0x80
	s_addc_u32 s5, s5, 0
	s_add_u32 s49, s49, 0x10000
	s_sub_u32 s53, s49, 0x28000
	s_cmp_ge_u32 s49, 0x28000
	s_cselect_b32 s49, s53, s49
	s_mov_b32 s50, s51
	s_waitcnt vmcnt(4)
	s_barrier
	v_add_u32_e32 v137, s50, v134
	v_add_u32_e32 v136, s49, v132
	ds_read_b128 v[164:167], v137
	ds_read_b128 v[168:171], v137 offset:2048
	ds_read_b128 v[172:175], v137 offset:4096
	ds_read_b128 v[176:179], v137 offset:6144
	ds_read_b128 v[224:227], v136
	ds_read_b128 v[228:231], v136 offset:2048
	ds_read_b128 v[232:235], v136 offset:4096
	ds_read_b128 v[236:239], v136 offset:6144
	s_cmpk_lg_i32 s4, 0xf00
	s_cbranch_scc1 .Lg161_loop
	s_add_u32 s51, s50, 0x10000
	s_sub_u32 s53, s51, 0x28000
	s_cmp_ge_u32 s51, 0x28000
	s_cselect_b32 s51, s53, s51
	v_add_u32_e32 v137, s50, v135
	s_waitcnt lgkmcnt(4)
	s_waitcnt lgkmcnt(3)
	v_mfma_f32_16x16x32_bf16 v[112:115], v[164:167], v[224:227], v[112:115]
	v_mfma_f32_16x16x32_bf16 v[120:123], v[168:171], v[224:227], v[120:123]
	v_mfma_f32_16x16x32_bf16 v[96:99], v[172:175], v[224:227], v[96:99]
	v_mfma_f32_16x16x32_bf16 v[104:107], v[176:179], v[224:227], v[104:107]
	s_add_u32 m0, s51, s48
	s_nop 0
	global_load_lds_dwordx4 v139, s[64:65]
	s_add_u32 s64, s64, 0x80
	s_addc_u32 s65, s65, 0
	s_add_u32 s53, s51, s48
	s_add_u32 m0, s53, 0x2000
	s_nop 0
	global_load_lds_dwordx4 v139, s[66:67]
	s_add_u32 s66, s66, 0x80
	s_addc_u32 s67, s67, 0
	ds_read_b128 v[224:227], v136 offset:8192
	ds_read_b128 v[180:183], v137
	s_waitcnt lgkmcnt(4)
	v_mfma_f32_16x16x32_bf16 v[116:119], v[164:167], v[228:231], v[116:119]
	v_mfma_f32_16x16x32_bf16 v[124:127], v[168:171], v[228:231], v[124:127]
	v_mfma_f32_16x16x32_bf16 v[100:103], v[172:175], v[228:231], v[100:103]
	v_mfma_f32_16x16x32_bf16 v[108:111], v[176:179], v[228:231], v[108:111]
	s_add_u32 s53, s51, s48
	s_add_u32 m0, s53, 0x4000
	s_nop 0
	global_load_lds_dwordx4 v139, s[68:69]
	s_add_u32 s68, s68, 0x80
	s_addc_u32 s69, s69, 0
	s_add_u32 s53, s51, s48
	s_add_u32 m0, s53, 0x6000
	s_nop 0
	global_load_lds_dwordx4 v139, s[70:71]
	s_add_u32 s70, s70, 0x80
	s_addc_u32 s71, s71, 0
	ds_read_b128 v[228:231], v136 offset:10240
	ds_read_b128 v[212:215], v137 offset:2048
	s_waitcnt lgkmcnt(5)
	v_mfma_f32_16x16x32_bf16 v[80:83], v[164:167], v[232:235], v[80:83]
	v_mfma_f32_16x16x32_bf16 v[88:91], v[168:171], v[232:235], v[88:91]
	v_mfma_f32_16x16x32_bf16 v[64:67], v[172:175], v[232:235], v[64:67]
	v_mfma_f32_16x16x32_bf16 v[72:75], v[176:179], v[232:235], v[72:75]
	ds_read_b128 v[232:235], v136 offset:12288
	ds_read_b128 v[216:219], v137 offset:4096
	s_waitcnt lgkmcnt(6)
	v_mfma_f32_16x16x32_bf16 v[84:87], v[164:167], v[236:239], v[84:87]
	v_mfma_f32_16x16x32_bf16 v[92:95], v[168:171], v[236:239], v[92:95]
	v_mfma_f32_16x16x32_bf16 v[68:71], v[172:175], v[236:239], v[68:71]
	v_mfma_f32_16x16x32_bf16 v[76:79], v[176:179], v[236:239], v[76:79]
	ds_read_b128 v[236:239], v136 offset:14336
	ds_read_b128 v[220:223], v137 offset:6144
	v_add_u32_e32 v136, s49, v133
	s_waitcnt lgkmcnt(7)
	v_mfma_f32_16x16x32_bf16 v[48:51], v[164:167], v[224:227], v[48:51]
	v_mfma_f32_16x16x32_bf16 v[56:59], v[168:171], v[224:227], v[56:59]
	v_mfma_f32_16x16x32_bf16 v[32:35], v[172:175], v[224:227], v[32:35]
	v_mfma_f32_16x16x32_bf16 v[40:43], v[176:179], v[224:227], v[40:43]
	ds_read_b128 v[224:227], v136
	s_waitcnt lgkmcnt(6)
	v_mfma_f32_16x16x32_bf16 v[52:55], v[164:167], v[228:231], v[52:55]
	v_mfma_f32_16x16x32_bf16 v[60:63], v[168:171], v[228:231], v[60:63]
	v_mfma_f32_16x16x32_bf16 v[36:39], v[172:175], v[228:231], v[36:39]
	v_mfma_f32_16x16x32_bf16 v[44:47], v[176:179], v[228:231], v[44:47]
	ds_read_b128 v[228:231], v136 offset:2048
	s_waitcnt lgkmcnt(5)
	v_mfma_f32_16x16x32_bf16 v[16:19], v[164:167], v[232:235], v[16:19]
	v_mfma_f32_16x16x32_bf16 v[24:27], v[168:171], v[232:235], v[24:27]
	v_mfma_f32_16x16x32_bf16 v[0:3], v[172:175], v[232:235], v[0:3]
	v_mfma_f32_16x16x32_bf16 v[8:11], v[176:179], v[232:235], v[8:11]
	ds_read_b128 v[232:235], v136 offset:4096
	s_waitcnt lgkmcnt(4)
	v_mfma_f32_16x16x32_bf16 v[20:23], v[164:167], v[236:239], v[20:23]
	v_mfma_f32_16x16x32_bf16 v[28:31], v[168:171], v[236:239], v[28:31]
	v_mfma_f32_16x16x32_bf16 v[4:7], v[172:175], v[236:239], v[4:7]
	v_mfma_f32_16x16x32_bf16 v[12:15], v[176:179], v[236:239], v[12:15]
	ds_read_b128 v[236:239], v136 offset:6144
	s_waitcnt lgkmcnt(4)
	s_waitcnt lgkmcnt(3)
	v_mfma_f32_16x16x32_bf16 v[112:115], v[180:183], v[224:227], v[112:115]
	v_mfma_f32_16x16x32_bf16 v[120:123], v[212:215], v[224:227], v[120:123]
	v_mfma_f32_16x16x32_bf16 v[96:99], v[216:219], v[224:227], v[96:99]
	v_mfma_f32_16x16x32_bf16 v[104:107], v[220:223], v[224:227], v[104:107]
	ds_read_b128 v[224:227], v136 offset:8192
	s_waitcnt lgkmcnt(3)
	v_mfma_f32_16x16x32_bf16 v[116:119], v[180:183], v[228:231], v[116:119]
	v_mfma_f32_16x16x32_bf16 v[124:127], v[212:215], v[228:231], v[124:127]
	v_mfma_f32_16x16x32_bf16 v[100:103], v[216:219], v[228:231], v[100:103]
	v_mfma_f32_16x16x32_bf16 v[108:111], v[220:223], v[228:231], v[108:111]
	ds_read_b128 v[228:231], v136 offset:10240
	s_waitcnt lgkmcnt(3)
	v_mfma_f32_16x16x32_bf16 v[80:83], v[180:183], v[232:235], v[80:83]
	v_mfma_f32_16x16x32_bf16 v[88:91], v[212:215], v[232:235], v[88:91]
	v_mfma_f32_16x16x32_bf16 v[64:67], v[216:219], v[232:235], v[64:67]
	v_mfma_f32_16x16x32_bf16 v[72:75], v[220:223], v[232:235], v[72:75]
	ds_read_b128 v[232:235], v136 offset:12288
	s_waitcnt lgkmcnt(3)
	v_mfma_f32_16x16x32_bf16 v[84:87], v[180:183], v[236:239], v[84:87]
	v_mfma_f32_16x16x32_bf16 v[92:95], v[212:215], v[236:239], v[92:95]
	v_mfma_f32_16x16x32_bf16 v[68:71], v[216:219], v[236:239], v[68:71]
	v_mfma_f32_16x16x32_bf16 v[76:79], v[220:223], v[236:239], v[76:79]
	ds_read_b128 v[236:239], v136 offset:14336
	s_waitcnt lgkmcnt(3)
	v_mfma_f32_16x16x32_bf16 v[48:51], v[180:183], v[224:227], v[48:51]
	v_mfma_f32_16x16x32_bf16 v[56:59], v[212:215], v[224:227], v[56:59]
	v_mfma_f32_16x16x32_bf16 v[32:35], v[216:219], v[224:227], v[32:35]
	v_mfma_f32_16x16x32_bf16 v[40:43], v[220:223], v[224:227], v[40:43]
	s_waitcnt lgkmcnt(2)
	v_mfma_f32_16x16x32_bf16 v[52:55], v[180:183], v[228:231], v[52:55]
	v_mfma_f32_16x16x32_bf16 v[60:63], v[212:215], v[228:231], v[60:63]
	v_mfma_f32_16x16x32_bf16 v[36:39], v[216:219], v[228:231], v[36:39]
	v_mfma_f32_16x16x32_bf16 v[44:47], v[220:223], v[228:231], v[44:47]
	s_waitcnt lgkmcnt(1)
	v_mfma_f32_16x16x32_bf16 v[16:19], v[180:183], v[232:235], v[16:19]
	v_mfma_f32_16x16x32_bf16 v[24:27], v[212:215], v[232:235], v[24:27]
	v_mfma_f32_16x16x32_bf16 v[0:3], v[216:219], v[232:235], v[0:3]
	v_mfma_f32_16x16x32_bf16 v[8:11], v[220:223], v[232:235], v[8:11]
	s_waitcnt lgkmcnt(0)
	v_mfma_f32_16x16x32_bf16 v[20:23], v[180:183], v[236:239], v[20:23]
	v_mfma_f32_16x16x32_bf16 v[28:31], v[212:215], v[236:239], v[28:31]
	v_mfma_f32_16x16x32_bf16 v[4:7], v[216:219], v[236:239], v[4:7]
	v_mfma_f32_16x16x32_bf16 v[12:15], v[220:223], v[236:239], v[12:15]
	s_waitcnt lgkmcnt(0)
	s_add_u32 s4, s4, 0x80
	s_addc_u32 s5, s5, 0
	s_add_u32 s49, s49, 0x10000
	s_sub_u32 s53, s49, 0x28000
	s_cmp_ge_u32 s49, 0x28000
	s_cselect_b32 s49, s53, s49
	s_mov_b32 s50, s51
	s_waitcnt vmcnt(0)
	s_barrier
	v_add_u32_e32 v137, s50, v134
	v_add_u32_e32 v136, s49, v132
	ds_read_b128 v[164:167], v137
	ds_read_b128 v[168:171], v137 offset:2048
	ds_read_b128 v[172:175], v137 offset:4096
	ds_read_b128 v[176:179], v137 offset:6144
	ds_read_b128 v[224:227], v136
	ds_read_b128 v[228:231], v136 offset:2048
	ds_read_b128 v[232:235], v136 offset:4096
	ds_read_b128 v[236:239], v136 offset:6144
	v_add_u32_e32 v137, s50, v135
	s_waitcnt lgkmcnt(4)
	s_waitcnt lgkmcnt(3)
	v_mfma_f32_16x16x32_bf16 v[112:115], v[164:167], v[224:227], v[112:115]
	v_mfma_f32_16x16x32_bf16 v[120:123], v[168:171], v[224:227], v[120:123]
	v_mfma_f32_16x16x32_bf16 v[96:99], v[172:175], v[224:227], v[96:99]
	v_mfma_f32_16x16x32_bf16 v[104:107], v[176:179], v[224:227], v[104:107]
	ds_read_b128 v[224:227], v136 offset:8192
	ds_read_b128 v[180:183], v137
	s_waitcnt lgkmcnt(4)
	v_mfma_f32_16x16x32_bf16 v[116:119], v[164:167], v[228:231], v[116:119]
	v_mfma_f32_16x16x32_bf16 v[124:127], v[168:171], v[228:231], v[124:127]
	v_mfma_f32_16x16x32_bf16 v[100:103], v[172:175], v[228:231], v[100:103]
	v_mfma_f32_16x16x32_bf16 v[108:111], v[176:179], v[228:231], v[108:111]
	ds_read_b128 v[228:231], v136 offset:10240
	ds_read_b128 v[212:215], v137 offset:2048
	s_waitcnt lgkmcnt(5)
	v_mfma_f32_16x16x32_bf16 v[80:83], v[164:167], v[232:235], v[80:83]
	v_mfma_f32_16x16x32_bf16 v[88:91], v[168:171], v[232:235], v[88:91]
	v_mfma_f32_16x16x32_bf16 v[64:67], v[172:175], v[232:235], v[64:67]
	v_mfma_f32_16x16x32_bf16 v[72:75], v[176:179], v[232:235], v[72:75]
	ds_read_b128 v[232:235], v136 offset:12288
	ds_read_b128 v[216:219], v137 offset:4096
	s_waitcnt lgkmcnt(6)
	v_mfma_f32_16x16x32_bf16 v[84:87], v[164:167], v[236:239], v[84:87]
	v_mfma_f32_16x16x32_bf16 v[92:95], v[168:171], v[236:239], v[92:95]
	v_mfma_f32_16x16x32_bf16 v[68:71], v[172:175], v[236:239], v[68:71]
	v_mfma_f32_16x16x32_bf16 v[76:79], v[176:179], v[236:239], v[76:79]
	ds_read_b128 v[236:239], v136 offset:14336
	ds_read_b128 v[220:223], v137 offset:6144
	v_add_u32_e32 v136, s49, v133
	s_waitcnt lgkmcnt(7)
	v_mfma_f32_16x16x32_bf16 v[48:51], v[164:167], v[224:227], v[48:51]
	v_mfma_f32_16x16x32_bf16 v[56:59], v[168:171], v[224:227], v[56:59]
	v_mfma_f32_16x16x32_bf16 v[32:35], v[172:175], v[224:227], v[32:35]
	v_mfma_f32_16x16x32_bf16 v[40:43], v[176:179], v[224:227], v[40:43]
	ds_read_b128 v[224:227], v136
	s_waitcnt lgkmcnt(6)
	v_mfma_f32_16x16x32_bf16 v[52:55], v[164:167], v[228:231], v[52:55]
	v_mfma_f32_16x16x32_bf16 v[60:63], v[168:171], v[228:231], v[60:63]
	v_mfma_f32_16x16x32_bf16 v[36:39], v[172:175], v[228:231], v[36:39]
	v_mfma_f32_16x16x32_bf16 v[44:47], v[176:179], v[228:231], v[44:47]
	ds_read_b128 v[228:231], v136 offset:2048
	s_waitcnt lgkmcnt(5)
	v_mfma_f32_16x16x32_bf16 v[16:19], v[164:167], v[232:235], v[16:19]
	v_mfma_f32_16x16x32_bf16 v[24:27], v[168:171], v[232:235], v[24:27]
	v_mfma_f32_16x16x32_bf16 v[0:3], v[172:175], v[232:235], v[0:3]
	v_mfma_f32_16x16x32_bf16 v[8:11], v[176:179], v[232:235], v[8:11]
	ds_read_b128 v[232:235], v136 offset:4096
	s_waitcnt lgkmcnt(4)
	v_mfma_f32_16x16x32_bf16 v[20:23], v[164:167], v[236:239], v[20:23]
	v_mfma_f32_16x16x32_bf16 v[28:31], v[168:171], v[236:239], v[28:31]
	v_mfma_f32_16x16x32_bf16 v[4:7], v[172:175], v[236:239], v[4:7]
	v_mfma_f32_16x16x32_bf16 v[12:15], v[176:179], v[236:239], v[12:15]
	ds_read_b128 v[236:239], v136 offset:6144
	s_waitcnt lgkmcnt(4)
	s_waitcnt lgkmcnt(3)
	v_mfma_f32_16x16x32_bf16 v[112:115], v[180:183], v[224:227], v[112:115]
	v_mfma_f32_16x16x32_bf16 v[120:123], v[212:215], v[224:227], v[120:123]
	v_mfma_f32_16x16x32_bf16 v[96:99], v[216:219], v[224:227], v[96:99]
	v_mfma_f32_16x16x32_bf16 v[104:107], v[220:223], v[224:227], v[104:107]
	ds_read_b128 v[224:227], v136 offset:8192
	s_waitcnt lgkmcnt(3)
	v_mfma_f32_16x16x32_bf16 v[116:119], v[180:183], v[228:231], v[116:119]
	v_mfma_f32_16x16x32_bf16 v[124:127], v[212:215], v[228:231], v[124:127]
	v_mfma_f32_16x16x32_bf16 v[100:103], v[216:219], v[228:231], v[100:103]
	v_mfma_f32_16x16x32_bf16 v[108:111], v[220:223], v[228:231], v[108:111]
	ds_read_b128 v[228:231], v136 offset:10240
	s_waitcnt lgkmcnt(3)
	v_mfma_f32_16x16x32_bf16 v[80:83], v[180:183], v[232:235], v[80:83]
	v_mfma_f32_16x16x32_bf16 v[88:91], v[212:215], v[232:235], v[88:91]
	v_mfma_f32_16x16x32_bf16 v[64:67], v[216:219], v[232:235], v[64:67]
	v_mfma_f32_16x16x32_bf16 v[72:75], v[220:223], v[232:235], v[72:75]
	ds_read_b128 v[232:235], v136 offset:12288
	s_waitcnt lgkmcnt(3)
	v_mfma_f32_16x16x32_bf16 v[84:87], v[180:183], v[236:239], v[84:87]
	v_mfma_f32_16x16x32_bf16 v[92:95], v[212:215], v[236:239], v[92:95]
	v_mfma_f32_16x16x32_bf16 v[68:71], v[216:219], v[236:239], v[68:71]
	v_mfma_f32_16x16x32_bf16 v[76:79], v[220:223], v[236:239], v[76:79]
	ds_read_b128 v[236:239], v136 offset:14336
	s_waitcnt lgkmcnt(3)
	v_mfma_f32_16x16x32_bf16 v[48:51], v[180:183], v[224:227], v[48:51]
	v_mfma_f32_16x16x32_bf16 v[56:59], v[212:215], v[224:227], v[56:59]
	v_mfma_f32_16x16x32_bf16 v[32:35], v[216:219], v[224:227], v[32:35]
	v_mfma_f32_16x16x32_bf16 v[40:43], v[220:223], v[224:227], v[40:43]
	s_waitcnt lgkmcnt(2)
	v_mfma_f32_16x16x32_bf16 v[52:55], v[180:183], v[228:231], v[52:55]
	v_mfma_f32_16x16x32_bf16 v[60:63], v[212:215], v[228:231], v[60:63]
	v_mfma_f32_16x16x32_bf16 v[36:39], v[216:219], v[228:231], v[36:39]
	v_mfma_f32_16x16x32_bf16 v[44:47], v[220:223], v[228:231], v[44:47]
	s_waitcnt lgkmcnt(1)
	v_mfma_f32_16x16x32_bf16 v[16:19], v[180:183], v[232:235], v[16:19]
	v_mfma_f32_16x16x32_bf16 v[24:27], v[212:215], v[232:235], v[24:27]
	v_mfma_f32_16x16x32_bf16 v[0:3], v[216:219], v[232:235], v[0:3]
	v_mfma_f32_16x16x32_bf16 v[8:11], v[220:223], v[232:235], v[8:11]
	s_waitcnt lgkmcnt(0)
	v_mfma_f32_16x16x32_bf16 v[20:23], v[180:183], v[236:239], v[20:23]
	v_mfma_f32_16x16x32_bf16 v[28:31], v[212:215], v[236:239], v[28:31]
	v_mfma_f32_16x16x32_bf16 v[4:7], v[216:219], v[236:239], v[4:7]
	v_mfma_f32_16x16x32_bf16 v[12:15], v[220:223], v[236:239], v[12:15]
	s_waitcnt lgkmcnt(0)
	s_waitcnt vmcnt(0)
	s_barrier
	s_nop 15
	v_permlane16_swap_b32_e32 v112, v116
	v_permlane16_swap_b32_e32 v113, v117
	v_permlane16_swap_b32_e32 v114, v118
	v_permlane16_swap_b32_e32 v115, v119
	v_permlane16_swap_b32_e32 v120, v124
	v_permlane16_swap_b32_e32 v121, v125
	v_permlane16_swap_b32_e32 v122, v126
	v_permlane16_swap_b32_e32 v123, v127
	v_permlane16_swap_b32_e32 v96, v100
	v_permlane16_swap_b32_e32 v97, v101
	v_permlane16_swap_b32_e32 v98, v102
	v_permlane16_swap_b32_e32 v99, v103
	v_permlane16_swap_b32_e32 v104, v108
	v_permlane16_swap_b32_e32 v105, v109
	v_permlane16_swap_b32_e32 v106, v110
	v_permlane16_swap_b32_e32 v107, v111
	v_permlane16_swap_b32_e32 v80, v84
	v_permlane16_swap_b32_e32 v81, v85
	v_permlane16_swap_b32_e32 v82, v86
	v_permlane16_swap_b32_e32 v83, v87
	v_permlane16_swap_b32_e32 v88, v92
	v_permlane16_swap_b32_e32 v89, v93
	v_permlane16_swap_b32_e32 v90, v94
	v_permlane16_swap_b32_e32 v91, v95
	v_permlane16_swap_b32_e32 v64, v68
	v_permlane16_swap_b32_e32 v65, v69
	v_permlane16_swap_b32_e32 v66, v70
	v_permlane16_swap_b32_e32 v67, v71
	v_permlane16_swap_b32_e32 v72, v76
	v_permlane16_swap_b32_e32 v73, v77
	v_permlane16_swap_b32_e32 v74, v78
	v_permlane16_swap_b32_e32 v75, v79
	v_permlane16_swap_b32_e32 v48, v52
	v_permlane16_swap_b32_e32 v49, v53
	v_permlane16_swap_b32_e32 v50, v54
	v_permlane16_swap_b32_e32 v51, v55
	v_permlane16_swap_b32_e32 v56, v60
	v_permlane16_swap_b32_e32 v57, v61
	v_permlane16_swap_b32_e32 v58, v62
	v_permlane16_swap_b32_e32 v59, v63
	v_permlane16_swap_b32_e32 v32, v36
	v_permlane16_swap_b32_e32 v33, v37
	v_permlane16_swap_b32_e32 v34, v38
	v_permlane16_swap_b32_e32 v35, v39
	v_permlane16_swap_b32_e32 v40, v44
	v_permlane16_swap_b32_e32 v41, v45
	v_permlane16_swap_b32_e32 v42, v46
	v_permlane16_swap_b32_e32 v43, v47
	v_permlane16_swap_b32_e32 v16, v20
	v_permlane16_swap_b32_e32 v17, v21
	v_permlane16_swap_b32_e32 v18, v22
	v_permlane16_swap_b32_e32 v19, v23
	v_permlane16_swap_b32_e32 v24, v28
	v_permlane16_swap_b32_e32 v25, v29
	v_permlane16_swap_b32_e32 v26, v30
	v_permlane16_swap_b32_e32 v27, v31
	v_permlane16_swap_b32_e32 v0, v4
	v_permlane16_swap_b32_e32 v1, v5
	v_permlane16_swap_b32_e32 v2, v6
	v_permlane16_swap_b32_e32 v3, v7
	v_permlane16_swap_b32_e32 v8, v12
	v_permlane16_swap_b32_e32 v9, v13
	v_permlane16_swap_b32_e32 v10, v14
	v_permlane16_swap_b32_e32 v11, v15
	v_permlane32_swap_b32_e32 v112, v116
	v_permlane32_swap_b32_e32 v113, v117
	v_permlane32_swap_b32_e32 v114, v118
	v_permlane32_swap_b32_e32 v115, v119
	v_permlane32_swap_b32_e32 v120, v124
	v_permlane32_swap_b32_e32 v121, v125
	v_permlane32_swap_b32_e32 v122, v126
	v_permlane32_swap_b32_e32 v123, v127
	v_permlane32_swap_b32_e32 v96, v100
	v_permlane32_swap_b32_e32 v97, v101
	v_permlane32_swap_b32_e32 v98, v102
	v_permlane32_swap_b32_e32 v99, v103
	v_permlane32_swap_b32_e32 v104, v108
	v_permlane32_swap_b32_e32 v105, v109
	v_permlane32_swap_b32_e32 v106, v110
	v_permlane32_swap_b32_e32 v107, v111
	v_permlane32_swap_b32_e32 v80, v84
	v_permlane32_swap_b32_e32 v81, v85
	v_permlane32_swap_b32_e32 v82, v86
	v_permlane32_swap_b32_e32 v83, v87
	v_permlane32_swap_b32_e32 v88, v92
	v_permlane32_swap_b32_e32 v89, v93
	v_permlane32_swap_b32_e32 v90, v94
	v_permlane32_swap_b32_e32 v91, v95
	v_permlane32_swap_b32_e32 v64, v68
	v_permlane32_swap_b32_e32 v65, v69
	v_permlane32_swap_b32_e32 v66, v70
	v_permlane32_swap_b32_e32 v67, v71
	v_permlane32_swap_b32_e32 v72, v76
	v_permlane32_swap_b32_e32 v73, v77
	v_permlane32_swap_b32_e32 v74, v78
	v_permlane32_swap_b32_e32 v75, v79
	v_permlane32_swap_b32_e32 v48, v52
	v_permlane32_swap_b32_e32 v49, v53
	v_permlane32_swap_b32_e32 v50, v54
	v_permlane32_swap_b32_e32 v51, v55
	v_permlane32_swap_b32_e32 v56, v60
	v_permlane32_swap_b32_e32 v57, v61
	v_permlane32_swap_b32_e32 v58, v62
	v_permlane32_swap_b32_e32 v59, v63
	v_permlane32_swap_b32_e32 v32, v36
	v_permlane32_swap_b32_e32 v33, v37
	v_permlane32_swap_b32_e32 v34, v38
	v_permlane32_swap_b32_e32 v35, v39
	v_permlane32_swap_b32_e32 v40, v44
	v_permlane32_swap_b32_e32 v41, v45
	v_permlane32_swap_b32_e32 v42, v46
	v_permlane32_swap_b32_e32 v43, v47
	v_permlane32_swap_b32_e32 v16, v20
	v_permlane32_swap_b32_e32 v17, v21
	v_permlane32_swap_b32_e32 v18, v22
	v_permlane32_swap_b32_e32 v19, v23
	v_permlane32_swap_b32_e32 v24, v28
	v_permlane32_swap_b32_e32 v25, v29
	v_permlane32_swap_b32_e32 v26, v30
	v_permlane32_swap_b32_e32 v27, v31
	v_permlane32_swap_b32_e32 v0, v4
	v_permlane32_swap_b32_e32 v1, v5
	v_permlane32_swap_b32_e32 v2, v6
	v_permlane32_swap_b32_e32 v3, v7
	v_permlane32_swap_b32_e32 v8, v12
	v_permlane32_swap_b32_e32 v9, v13
	v_permlane32_swap_b32_e32 v10, v14
	v_permlane32_swap_b32_e32 v11, v15
	s_nop 1

.Lg162_loop:
	s_add_u32 s51, s50, 0x10000
	s_sub_u32 s53, s51, 0x28000
	s_cmp_ge_u32 s51, 0x28000
	s_cselect_b32 s51, s53, s51
	s_add_u32 s52, s49, 0x20000
	s_sub_u32 s53, s52, 0x28000
	s_cmp_ge_u32 s52, 0x28000
	s_cselect_b32 s52, s53, s52
	v_add_u32_e32 v167, s50, v145
	s_waitcnt lgkmcnt(4)
	s_waitcnt lgkmcnt(3)
	v_mfma_f32_16x16x32_bf16 v[112:115], v[188:191], v[220:223], v[112:115]
	v_mfma_f32_16x16x32_bf16 v[120:123], v[192:195], v[220:223], v[120:123]
	v_mfma_f32_16x16x32_bf16 v[96:99], v[196:199], v[220:223], v[96:99]
	v_mfma_f32_16x16x32_bf16 v[104:107], v[200:203], v[220:223], v[104:107]
	s_add_u32 m0, s51, s48
	s_nop 0
	global_load_lds_dwordx4 v169, s[64:65]
	s_add_u32 s64, s64, 0x80
	s_addc_u32 s65, s65, 0
	s_add_u32 s53, s51, s48
	s_add_u32 m0, s53, 0x2000
	s_nop 0
	global_load_lds_dwordx4 v169, s[66:67]
	s_add_u32 s66, s66, 0x80
	s_addc_u32 s67, s67, 0
	ds_read_b128 v[220:223], v166 offset:8192
	ds_read_b128 v[204:207], v167
	s_waitcnt lgkmcnt(4)
	v_mfma_f32_16x16x32_bf16 v[116:119], v[188:191], v[224:227], v[116:119]
	v_mfma_f32_16x16x32_bf16 v[124:127], v[192:195], v[224:227], v[124:127]
	v_mfma_f32_16x16x32_bf16 v[100:103], v[196:199], v[224:227], v[100:103]
	v_mfma_f32_16x16x32_bf16 v[108:111], v[200:203], v[224:227], v[108:111]
	s_add_u32 s53, s51, s48
	s_add_u32 m0, s53, 0x4000
	s_nop 0
	global_load_lds_dwordx4 v169, s[68:69]
	s_add_u32 s68, s68, 0x80
	s_addc_u32 s69, s69, 0
	s_add_u32 s53, s51, s48
	s_add_u32 m0, s53, 0x6000
	s_nop 0
	global_load_lds_dwordx4 v169, s[70:71]
	s_add_u32 s70, s70, 0x80
	s_addc_u32 s71, s71, 0
	ds_read_b128 v[224:227], v166 offset:10240
	ds_read_b128 v[208:211], v167 offset:2048
	s_waitcnt lgkmcnt(5)
	v_mfma_f32_16x16x32_bf16 v[80:83], v[188:191], v[228:231], v[80:83]
	v_mfma_f32_16x16x32_bf16 v[88:91], v[192:195], v[228:231], v[88:91]
	v_mfma_f32_16x16x32_bf16 v[64:67], v[196:199], v[228:231], v[64:67]
	v_mfma_f32_16x16x32_bf16 v[72:75], v[200:203], v[228:231], v[72:75]
	ds_read_b128 v[228:231], v166 offset:12288
	ds_read_b128 v[212:215], v167 offset:4096
	s_waitcnt lgkmcnt(6)
	v_mfma_f32_16x16x32_bf16 v[84:87], v[188:191], v[232:235], v[84:87]
	v_mfma_f32_16x16x32_bf16 v[92:95], v[192:195], v[232:235], v[92:95]
	v_mfma_f32_16x16x32_bf16 v[68:71], v[196:199], v[232:235], v[68:71]
	v_mfma_f32_16x16x32_bf16 v[76:79], v[200:203], v[232:235], v[76:79]
	ds_read_b128 v[232:235], v166 offset:14336
	ds_read_b128 v[216:219], v167 offset:6144
	v_add_u32_e32 v166, s49, v143
	s_waitcnt lgkmcnt(7)
	v_mfma_f32_16x16x32_bf16 v[48:51], v[188:191], v[220:223], v[48:51]
	v_mfma_f32_16x16x32_bf16 v[56:59], v[192:195], v[220:223], v[56:59]
	v_mfma_f32_16x16x32_bf16 v[32:35], v[196:199], v[220:223], v[32:35]
	v_mfma_f32_16x16x32_bf16 v[40:43], v[200:203], v[220:223], v[40:43]
	ds_read_b128 v[220:223], v166
	s_waitcnt lgkmcnt(6)
	v_mfma_f32_16x16x32_bf16 v[52:55], v[188:191], v[224:227], v[52:55]
	v_mfma_f32_16x16x32_bf16 v[60:63], v[192:195], v[224:227], v[60:63]
	v_mfma_f32_16x16x32_bf16 v[36:39], v[196:199], v[224:227], v[36:39]
	v_mfma_f32_16x16x32_bf16 v[44:47], v[200:203], v[224:227], v[44:47]
	ds_read_b128 v[224:227], v166 offset:2048
	s_waitcnt lgkmcnt(5)
	v_mfma_f32_16x16x32_bf16 v[16:19], v[188:191], v[228:231], v[16:19]
	v_mfma_f32_16x16x32_bf16 v[24:27], v[192:195], v[228:231], v[24:27]
	v_mfma_f32_16x16x32_bf16 v[0:3], v[196:199], v[228:231], v[0:3]
	v_mfma_f32_16x16x32_bf16 v[8:11], v[200:203], v[228:231], v[8:11]
	ds_read_b128 v[228:231], v166 offset:4096
	s_waitcnt lgkmcnt(4)
	v_mfma_f32_16x16x32_bf16 v[20:23], v[188:191], v[232:235], v[20:23]
	v_mfma_f32_16x16x32_bf16 v[28:31], v[192:195], v[232:235], v[28:31]
	v_mfma_f32_16x16x32_bf16 v[4:7], v[196:199], v[232:235], v[4:7]
	v_mfma_f32_16x16x32_bf16 v[12:15], v[200:203], v[232:235], v[12:15]
	ds_read_b128 v[232:235], v166 offset:6144
	s_waitcnt lgkmcnt(4)
	s_waitcnt lgkmcnt(3)
	v_mfma_f32_16x16x32_bf16 v[112:115], v[204:207], v[220:223], v[112:115]
	v_mfma_f32_16x16x32_bf16 v[120:123], v[208:211], v[220:223], v[120:123]
	v_mfma_f32_16x16x32_bf16 v[96:99], v[212:215], v[220:223], v[96:99]
	v_mfma_f32_16x16x32_bf16 v[104:107], v[216:219], v[220:223], v[104:107]
	ds_read_b128 v[220:223], v166 offset:8192
	s_waitcnt lgkmcnt(3)
	v_mfma_f32_16x16x32_bf16 v[116:119], v[204:207], v[224:227], v[116:119]
	v_mfma_f32_16x16x32_bf16 v[124:127], v[208:211], v[224:227], v[124:127]
	v_mfma_f32_16x16x32_bf16 v[100:103], v[212:215], v[224:227], v[100:103]
	v_mfma_f32_16x16x32_bf16 v[108:111], v[216:219], v[224:227], v[108:111]
	ds_read_b128 v[224:227], v166 offset:10240
	s_waitcnt lgkmcnt(3)
	v_mfma_f32_16x16x32_bf16 v[80:83], v[204:207], v[228:231], v[80:83]
	v_mfma_f32_16x16x32_bf16 v[88:91], v[208:211], v[228:231], v[88:91]
	v_mfma_f32_16x16x32_bf16 v[64:67], v[212:215], v[228:231], v[64:67]
	v_mfma_f32_16x16x32_bf16 v[72:75], v[216:219], v[228:231], v[72:75]
	ds_read_b128 v[228:231], v166 offset:12288
	s_waitcnt lgkmcnt(3)
	v_mfma_f32_16x16x32_bf16 v[84:87], v[204:207], v[232:235], v[84:87]
	v_mfma_f32_16x16x32_bf16 v[92:95], v[208:211], v[232:235], v[92:95]
	v_mfma_f32_16x16x32_bf16 v[68:71], v[212:215], v[232:235], v[68:71]
	v_mfma_f32_16x16x32_bf16 v[76:79], v[216:219], v[232:235], v[76:79]
	ds_read_b128 v[232:235], v166 offset:14336
	s_waitcnt lgkmcnt(3)
	v_mfma_f32_16x16x32_bf16 v[48:51], v[204:207], v[220:223], v[48:51]
	v_mfma_f32_16x16x32_bf16 v[56:59], v[208:211], v[220:223], v[56:59]
	v_mfma_f32_16x16x32_bf16 v[32:35], v[212:215], v[220:223], v[32:35]
	v_mfma_f32_16x16x32_bf16 v[40:43], v[216:219], v[220:223], v[40:43]
	s_add_u32 m0, s52, s48
	s_nop 0
	global_load_lds_dwordx4 v168, s[56:57]
	s_add_u32 s56, s56, 0x80
	s_addc_u32 s57, s57, 0
	s_add_u32 s53, s52, s48
	s_add_u32 m0, s53, 0x2000
	s_nop 0
	global_load_lds_dwordx4 v168, s[58:59]
	s_add_u32 s58, s58, 0x80
	s_addc_u32 s59, s59, 0
	s_waitcnt lgkmcnt(2)
	v_mfma_f32_16x16x32_bf16 v[52:55], v[204:207], v[224:227], v[52:55]
	v_mfma_f32_16x16x32_bf16 v[60:63], v[208:211], v[224:227], v[60:63]
	v_mfma_f32_16x16x32_bf16 v[36:39], v[212:215], v[224:227], v[36:39]
	v_mfma_f32_16x16x32_bf16 v[44:47], v[216:219], v[224:227], v[44:47]
	s_add_u32 s53, s52, s48
	s_add_u32 m0, s53, 0x4000
	s_nop 0
	global_load_lds_dwordx4 v168, s[60:61]
	s_add_u32 s60, s60, 0x80
	s_addc_u32 s61, s61, 0
	s_add_u32 s53, s52, s48
	s_add_u32 m0, s53, 0x6000
	s_nop 0
	global_load_lds_dwordx4 v168, s[62:63]
	s_add_u32 s62, s62, 0x80
	s_addc_u32 s63, s63, 0
	s_waitcnt lgkmcnt(1)
	v_mfma_f32_16x16x32_bf16 v[16:19], v[204:207], v[228:231], v[16:19]
	v_mfma_f32_16x16x32_bf16 v[24:27], v[208:211], v[228:231], v[24:27]
	v_mfma_f32_16x16x32_bf16 v[0:3], v[212:215], v[228:231], v[0:3]
	v_mfma_f32_16x16x32_bf16 v[8:11], v[216:219], v[228:231], v[8:11]
	s_waitcnt lgkmcnt(0)
	v_mfma_f32_16x16x32_bf16 v[20:23], v[204:207], v[232:235], v[20:23]
	v_mfma_f32_16x16x32_bf16 v[28:31], v[208:211], v[232:235], v[28:31]
	v_mfma_f32_16x16x32_bf16 v[4:7], v[212:215], v[232:235], v[4:7]
	v_mfma_f32_16x16x32_bf16 v[12:15], v[216:219], v[232:235], v[12:15]
	s_waitcnt lgkmcnt(0)
	s_add_u32 s28, s28, 0x80
	s_addc_u32 s29, s29, 0
	s_add_u32 s49, s49, 0x10000
	s_sub_u32 s53, s49, 0x28000
	s_cmp_ge_u32 s49, 0x28000
	s_cselect_b32 s49, s53, s49
	s_mov_b32 s50, s51
	s_waitcnt vmcnt(4)
	s_barrier
	v_add_u32_e32 v167, s50, v144
	v_add_u32_e32 v166, s49, v142
	ds_read_b128 v[188:191], v167
	ds_read_b128 v[192:195], v167 offset:2048
	ds_read_b128 v[196:199], v167 offset:4096
	ds_read_b128 v[200:203], v167 offset:6144
	ds_read_b128 v[220:223], v166
	ds_read_b128 v[224:227], v166 offset:2048
	ds_read_b128 v[228:231], v166 offset:4096
	ds_read_b128 v[232:235], v166 offset:6144
	s_cmpk_lg_i32 s28, 0xf00
	s_cbranch_scc1 .Lg162_loop
	s_add_u32 s51, s50, 0x10000
	s_sub_u32 s53, s51, 0x28000
	s_cmp_ge_u32 s51, 0x28000
	s_cselect_b32 s51, s53, s51
	v_add_u32_e32 v167, s50, v145
	s_waitcnt lgkmcnt(4)
	s_waitcnt lgkmcnt(3)
	v_mfma_f32_16x16x32_bf16 v[112:115], v[188:191], v[220:223], v[112:115]
	v_mfma_f32_16x16x32_bf16 v[120:123], v[192:195], v[220:223], v[120:123]
	v_mfma_f32_16x16x32_bf16 v[96:99], v[196:199], v[220:223], v[96:99]
	v_mfma_f32_16x16x32_bf16 v[104:107], v[200:203], v[220:223], v[104:107]
	s_add_u32 m0, s51, s48
	s_nop 0
	global_load_lds_dwordx4 v169, s[64:65]
	s_add_u32 s64, s64, 0x80
	s_addc_u32 s65, s65, 0
	s_add_u32 s53, s51, s48
	s_add_u32 m0, s53, 0x2000
	s_nop 0
	global_load_lds_dwordx4 v169, s[66:67]
	s_add_u32 s66, s66, 0x80
	s_addc_u32 s67, s67, 0
	ds_read_b128 v[220:223], v166 offset:8192
	ds_read_b128 v[204:207], v167
	s_waitcnt lgkmcnt(4)
	v_mfma_f32_16x16x32_bf16 v[116:119], v[188:191], v[224:227], v[116:119]
	v_mfma_f32_16x16x32_bf16 v[124:127], v[192:195], v[224:227], v[124:127]
	v_mfma_f32_16x16x32_bf16 v[100:103], v[196:199], v[224:227], v[100:103]
	v_mfma_f32_16x16x32_bf16 v[108:111], v[200:203], v[224:227], v[108:111]
	s_add_u32 s53, s51, s48
	s_add_u32 m0, s53, 0x4000
	s_nop 0
	global_load_lds_dwordx4 v169, s[68:69]
	s_add_u32 s68, s68, 0x80
	s_addc_u32 s69, s69, 0
	s_add_u32 s53, s51, s48
	s_add_u32 m0, s53, 0x6000
	s_nop 0
	global_load_lds_dwordx4 v169, s[70:71]
	s_add_u32 s70, s70, 0x80
	s_addc_u32 s71, s71, 0
	ds_read_b128 v[224:227], v166 offset:10240
	ds_read_b128 v[208:211], v167 offset:2048
	s_waitcnt lgkmcnt(5)
	v_mfma_f32_16x16x32_bf16 v[80:83], v[188:191], v[228:231], v[80:83]
	v_mfma_f32_16x16x32_bf16 v[88:91], v[192:195], v[228:231], v[88:91]
	v_mfma_f32_16x16x32_bf16 v[64:67], v[196:199], v[228:231], v[64:67]
	v_mfma_f32_16x16x32_bf16 v[72:75], v[200:203], v[228:231], v[72:75]
	ds_read_b128 v[228:231], v166 offset:12288
	ds_read_b128 v[212:215], v167 offset:4096
	s_waitcnt lgkmcnt(6)
	v_mfma_f32_16x16x32_bf16 v[84:87], v[188:191], v[232:235], v[84:87]
	v_mfma_f32_16x16x32_bf16 v[92:95], v[192:195], v[232:235], v[92:95]
	v_mfma_f32_16x16x32_bf16 v[68:71], v[196:199], v[232:235], v[68:71]
	v_mfma_f32_16x16x32_bf16 v[76:79], v[200:203], v[232:235], v[76:79]
	ds_read_b128 v[232:235], v166 offset:14336
	ds_read_b128 v[216:219], v167 offset:6144
	v_add_u32_e32 v166, s49, v143
	s_waitcnt lgkmcnt(7)
	v_mfma_f32_16x16x32_bf16 v[48:51], v[188:191], v[220:223], v[48:51]
	v_mfma_f32_16x16x32_bf16 v[56:59], v[192:195], v[220:223], v[56:59]
	v_mfma_f32_16x16x32_bf16 v[32:35], v[196:199], v[220:223], v[32:35]
	v_mfma_f32_16x16x32_bf16 v[40:43], v[200:203], v[220:223], v[40:43]
	ds_read_b128 v[220:223], v166
	s_waitcnt lgkmcnt(6)
	v_mfma_f32_16x16x32_bf16 v[52:55], v[188:191], v[224:227], v[52:55]
	v_mfma_f32_16x16x32_bf16 v[60:63], v[192:195], v[224:227], v[60:63]
	v_mfma_f32_16x16x32_bf16 v[36:39], v[196:199], v[224:227], v[36:39]
	v_mfma_f32_16x16x32_bf16 v[44:47], v[200:203], v[224:227], v[44:47]
	ds_read_b128 v[224:227], v166 offset:2048
	s_waitcnt lgkmcnt(5)
	v_mfma_f32_16x16x32_bf16 v[16:19], v[188:191], v[228:231], v[16:19]
	v_mfma_f32_16x16x32_bf16 v[24:27], v[192:195], v[228:231], v[24:27]
	v_mfma_f32_16x16x32_bf16 v[0:3], v[196:199], v[228:231], v[0:3]
	v_mfma_f32_16x16x32_bf16 v[8:11], v[200:203], v[228:231], v[8:11]
	ds_read_b128 v[228:231], v166 offset:4096
	s_waitcnt lgkmcnt(4)
	v_mfma_f32_16x16x32_bf16 v[20:23], v[188:191], v[232:235], v[20:23]
	v_mfma_f32_16x16x32_bf16 v[28:31], v[192:195], v[232:235], v[28:31]
	v_mfma_f32_16x16x32_bf16 v[4:7], v[196:199], v[232:235], v[4:7]
	v_mfma_f32_16x16x32_bf16 v[12:15], v[200:203], v[232:235], v[12:15]
	ds_read_b128 v[232:235], v166 offset:6144
	s_waitcnt lgkmcnt(4)
	s_waitcnt lgkmcnt(3)
	v_mfma_f32_16x16x32_bf16 v[112:115], v[204:207], v[220:223], v[112:115]
	v_mfma_f32_16x16x32_bf16 v[120:123], v[208:211], v[220:223], v[120:123]
	v_mfma_f32_16x16x32_bf16 v[96:99], v[212:215], v[220:223], v[96:99]
	v_mfma_f32_16x16x32_bf16 v[104:107], v[216:219], v[220:223], v[104:107]
	ds_read_b128 v[220:223], v166 offset:8192
	s_waitcnt lgkmcnt(3)
	v_mfma_f32_16x16x32_bf16 v[116:119], v[204:207], v[224:227], v[116:119]
	v_mfma_f32_16x16x32_bf16 v[124:127], v[208:211], v[224:227], v[124:127]
	v_mfma_f32_16x16x32_bf16 v[100:103], v[212:215], v[224:227], v[100:103]
	v_mfma_f32_16x16x32_bf16 v[108:111], v[216:219], v[224:227], v[108:111]
	ds_read_b128 v[224:227], v166 offset:10240
	s_waitcnt lgkmcnt(3)
	v_mfma_f32_16x16x32_bf16 v[80:83], v[204:207], v[228:231], v[80:83]
	v_mfma_f32_16x16x32_bf16 v[88:91], v[208:211], v[228:231], v[88:91]
	v_mfma_f32_16x16x32_bf16 v[64:67], v[212:215], v[228:231], v[64:67]
	v_mfma_f32_16x16x32_bf16 v[72:75], v[216:219], v[228:231], v[72:75]
	ds_read_b128 v[228:231], v166 offset:12288
	s_waitcnt lgkmcnt(3)
	v_mfma_f32_16x16x32_bf16 v[84:87], v[204:207], v[232:235], v[84:87]
	v_mfma_f32_16x16x32_bf16 v[92:95], v[208:211], v[232:235], v[92:95]
	v_mfma_f32_16x16x32_bf16 v[68:71], v[212:215], v[232:235], v[68:71]
	v_mfma_f32_16x16x32_bf16 v[76:79], v[216:219], v[232:235], v[76:79]
	ds_read_b128 v[232:235], v166 offset:14336
	s_waitcnt lgkmcnt(3)
	v_mfma_f32_16x16x32_bf16 v[48:51], v[204:207], v[220:223], v[48:51]
	v_mfma_f32_16x16x32_bf16 v[56:59], v[208:211], v[220:223], v[56:59]
	v_mfma_f32_16x16x32_bf16 v[32:35], v[212:215], v[220:223], v[32:35]
	v_mfma_f32_16x16x32_bf16 v[40:43], v[216:219], v[220:223], v[40:43]
	s_waitcnt lgkmcnt(2)
	v_mfma_f32_16x16x32_bf16 v[52:55], v[204:207], v[224:227], v[52:55]
	v_mfma_f32_16x16x32_bf16 v[60:63], v[208:211], v[224:227], v[60:63]
	v_mfma_f32_16x16x32_bf16 v[36:39], v[212:215], v[224:227], v[36:39]
	v_mfma_f32_16x16x32_bf16 v[44:47], v[216:219], v[224:227], v[44:47]
	s_waitcnt lgkmcnt(1)
	v_mfma_f32_16x16x32_bf16 v[16:19], v[204:207], v[228:231], v[16:19]
	v_mfma_f32_16x16x32_bf16 v[24:27], v[208:211], v[228:231], v[24:27]
	v_mfma_f32_16x16x32_bf16 v[0:3], v[212:215], v[228:231], v[0:3]
	v_mfma_f32_16x16x32_bf16 v[8:11], v[216:219], v[228:231], v[8:11]
	s_waitcnt lgkmcnt(0)
	v_mfma_f32_16x16x32_bf16 v[20:23], v[204:207], v[232:235], v[20:23]
	v_mfma_f32_16x16x32_bf16 v[28:31], v[208:211], v[232:235], v[28:31]
	v_mfma_f32_16x16x32_bf16 v[4:7], v[212:215], v[232:235], v[4:7]
	v_mfma_f32_16x16x32_bf16 v[12:15], v[216:219], v[232:235], v[12:15]
	s_waitcnt lgkmcnt(0)
	s_add_u32 s28, s28, 0x80
	s_addc_u32 s29, s29, 0
	s_add_u32 s49, s49, 0x10000
	s_sub_u32 s53, s49, 0x28000
	s_cmp_ge_u32 s49, 0x28000
	s_cselect_b32 s49, s53, s49
	s_mov_b32 s50, s51
	s_waitcnt vmcnt(0)
	s_barrier
	v_add_u32_e32 v167, s50, v144
	v_add_u32_e32 v166, s49, v142
	ds_read_b128 v[188:191], v167
	ds_read_b128 v[192:195], v167 offset:2048
	ds_read_b128 v[196:199], v167 offset:4096
	ds_read_b128 v[200:203], v167 offset:6144
	ds_read_b128 v[220:223], v166
	ds_read_b128 v[224:227], v166 offset:2048
	ds_read_b128 v[228:231], v166 offset:4096
	ds_read_b128 v[232:235], v166 offset:6144
	v_add_u32_e32 v167, s50, v145
	s_waitcnt lgkmcnt(4)
	s_waitcnt lgkmcnt(3)
	v_mfma_f32_16x16x32_bf16 v[112:115], v[188:191], v[220:223], v[112:115]
	v_mfma_f32_16x16x32_bf16 v[120:123], v[192:195], v[220:223], v[120:123]
	v_mfma_f32_16x16x32_bf16 v[96:99], v[196:199], v[220:223], v[96:99]
	v_mfma_f32_16x16x32_bf16 v[104:107], v[200:203], v[220:223], v[104:107]
	ds_read_b128 v[220:223], v166 offset:8192
	ds_read_b128 v[204:207], v167
	s_waitcnt lgkmcnt(4)
	v_mfma_f32_16x16x32_bf16 v[116:119], v[188:191], v[224:227], v[116:119]
	v_mfma_f32_16x16x32_bf16 v[124:127], v[192:195], v[224:227], v[124:127]
	v_mfma_f32_16x16x32_bf16 v[100:103], v[196:199], v[224:227], v[100:103]
	v_mfma_f32_16x16x32_bf16 v[108:111], v[200:203], v[224:227], v[108:111]
	ds_read_b128 v[224:227], v166 offset:10240
	ds_read_b128 v[208:211], v167 offset:2048
	s_waitcnt lgkmcnt(5)
	v_mfma_f32_16x16x32_bf16 v[80:83], v[188:191], v[228:231], v[80:83]
	v_mfma_f32_16x16x32_bf16 v[88:91], v[192:195], v[228:231], v[88:91]
	v_mfma_f32_16x16x32_bf16 v[64:67], v[196:199], v[228:231], v[64:67]
	v_mfma_f32_16x16x32_bf16 v[72:75], v[200:203], v[228:231], v[72:75]
	ds_read_b128 v[228:231], v166 offset:12288
	ds_read_b128 v[212:215], v167 offset:4096
	s_waitcnt lgkmcnt(6)
	v_mfma_f32_16x16x32_bf16 v[84:87], v[188:191], v[232:235], v[84:87]
	v_mfma_f32_16x16x32_bf16 v[92:95], v[192:195], v[232:235], v[92:95]
	v_mfma_f32_16x16x32_bf16 v[68:71], v[196:199], v[232:235], v[68:71]
	v_mfma_f32_16x16x32_bf16 v[76:79], v[200:203], v[232:235], v[76:79]
	ds_read_b128 v[232:235], v166 offset:14336
	ds_read_b128 v[216:219], v167 offset:6144
	v_add_u32_e32 v166, s49, v143
	s_waitcnt lgkmcnt(7)
	v_mfma_f32_16x16x32_bf16 v[48:51], v[188:191], v[220:223], v[48:51]
	v_mfma_f32_16x16x32_bf16 v[56:59], v[192:195], v[220:223], v[56:59]
	v_mfma_f32_16x16x32_bf16 v[32:35], v[196:199], v[220:223], v[32:35]
	v_mfma_f32_16x16x32_bf16 v[40:43], v[200:203], v[220:223], v[40:43]
	ds_read_b128 v[220:223], v166
	s_waitcnt lgkmcnt(6)
	v_mfma_f32_16x16x32_bf16 v[52:55], v[188:191], v[224:227], v[52:55]
	v_mfma_f32_16x16x32_bf16 v[60:63], v[192:195], v[224:227], v[60:63]
	v_mfma_f32_16x16x32_bf16 v[36:39], v[196:199], v[224:227], v[36:39]
	v_mfma_f32_16x16x32_bf16 v[44:47], v[200:203], v[224:227], v[44:47]
	ds_read_b128 v[224:227], v166 offset:2048
	s_waitcnt lgkmcnt(5)
	v_mfma_f32_16x16x32_bf16 v[16:19], v[188:191], v[228:231], v[16:19]
	v_mfma_f32_16x16x32_bf16 v[24:27], v[192:195], v[228:231], v[24:27]
	v_mfma_f32_16x16x32_bf16 v[0:3], v[196:199], v[228:231], v[0:3]
	v_mfma_f32_16x16x32_bf16 v[8:11], v[200:203], v[228:231], v[8:11]
	ds_read_b128 v[228:231], v166 offset:4096
	s_waitcnt lgkmcnt(4)
	v_mfma_f32_16x16x32_bf16 v[20:23], v[188:191], v[232:235], v[20:23]
	v_mfma_f32_16x16x32_bf16 v[28:31], v[192:195], v[232:235], v[28:31]
	v_mfma_f32_16x16x32_bf16 v[4:7], v[196:199], v[232:235], v[4:7]
	v_mfma_f32_16x16x32_bf16 v[12:15], v[200:203], v[232:235], v[12:15]
	ds_read_b128 v[232:235], v166 offset:6144
	s_waitcnt lgkmcnt(4)
	s_waitcnt lgkmcnt(3)
	v_mfma_f32_16x16x32_bf16 v[112:115], v[204:207], v[220:223], v[112:115]
	v_mfma_f32_16x16x32_bf16 v[120:123], v[208:211], v[220:223], v[120:123]
	v_mfma_f32_16x16x32_bf16 v[96:99], v[212:215], v[220:223], v[96:99]
	v_mfma_f32_16x16x32_bf16 v[104:107], v[216:219], v[220:223], v[104:107]
	ds_read_b128 v[220:223], v166 offset:8192
	s_waitcnt lgkmcnt(3)
	v_mfma_f32_16x16x32_bf16 v[116:119], v[204:207], v[224:227], v[116:119]
	v_mfma_f32_16x16x32_bf16 v[124:127], v[208:211], v[224:227], v[124:127]
	v_mfma_f32_16x16x32_bf16 v[100:103], v[212:215], v[224:227], v[100:103]
	v_mfma_f32_16x16x32_bf16 v[108:111], v[216:219], v[224:227], v[108:111]
	ds_read_b128 v[224:227], v166 offset:10240
	s_waitcnt lgkmcnt(3)
	v_mfma_f32_16x16x32_bf16 v[80:83], v[204:207], v[228:231], v[80:83]
	v_mfma_f32_16x16x32_bf16 v[88:91], v[208:211], v[228:231], v[88:91]
	v_mfma_f32_16x16x32_bf16 v[64:67], v[212:215], v[228:231], v[64:67]
	v_mfma_f32_16x16x32_bf16 v[72:75], v[216:219], v[228:231], v[72:75]
	ds_read_b128 v[228:231], v166 offset:12288
	s_waitcnt lgkmcnt(3)
	v_mfma_f32_16x16x32_bf16 v[84:87], v[204:207], v[232:235], v[84:87]
	v_mfma_f32_16x16x32_bf16 v[92:95], v[208:211], v[232:235], v[92:95]
	v_mfma_f32_16x16x32_bf16 v[68:71], v[212:215], v[232:235], v[68:71]
	v_mfma_f32_16x16x32_bf16 v[76:79], v[216:219], v[232:235], v[76:79]
	ds_read_b128 v[232:235], v166 offset:14336
	s_waitcnt lgkmcnt(3)
	v_mfma_f32_16x16x32_bf16 v[48:51], v[204:207], v[220:223], v[48:51]
	v_mfma_f32_16x16x32_bf16 v[56:59], v[208:211], v[220:223], v[56:59]
	v_mfma_f32_16x16x32_bf16 v[32:35], v[212:215], v[220:223], v[32:35]
	v_mfma_f32_16x16x32_bf16 v[40:43], v[216:219], v[220:223], v[40:43]
	s_waitcnt lgkmcnt(2)
	v_mfma_f32_16x16x32_bf16 v[52:55], v[204:207], v[224:227], v[52:55]
	v_mfma_f32_16x16x32_bf16 v[60:63], v[208:211], v[224:227], v[60:63]
	v_mfma_f32_16x16x32_bf16 v[36:39], v[212:215], v[224:227], v[36:39]
	v_mfma_f32_16x16x32_bf16 v[44:47], v[216:219], v[224:227], v[44:47]
	s_waitcnt lgkmcnt(1)
	v_mfma_f32_16x16x32_bf16 v[16:19], v[204:207], v[228:231], v[16:19]
	v_mfma_f32_16x16x32_bf16 v[24:27], v[208:211], v[228:231], v[24:27]
	v_mfma_f32_16x16x32_bf16 v[0:3], v[212:215], v[228:231], v[0:3]
	v_mfma_f32_16x16x32_bf16 v[8:11], v[216:219], v[228:231], v[8:11]
	s_waitcnt lgkmcnt(0)
	v_mfma_f32_16x16x32_bf16 v[20:23], v[204:207], v[232:235], v[20:23]
	v_mfma_f32_16x16x32_bf16 v[28:31], v[208:211], v[232:235], v[28:31]
	v_mfma_f32_16x16x32_bf16 v[4:7], v[212:215], v[232:235], v[4:7]
	v_mfma_f32_16x16x32_bf16 v[12:15], v[216:219], v[232:235], v[12:15]
	s_waitcnt lgkmcnt(0)
	s_waitcnt vmcnt(0)
	s_barrier
	s_nop 15
	v_permlane16_swap_b32_e32 v112, v116
	v_permlane16_swap_b32_e32 v113, v117
	v_permlane16_swap_b32_e32 v114, v118
	v_permlane16_swap_b32_e32 v115, v119
	v_permlane16_swap_b32_e32 v120, v124
	v_permlane16_swap_b32_e32 v121, v125
	v_permlane16_swap_b32_e32 v122, v126
	v_permlane16_swap_b32_e32 v123, v127
	v_permlane16_swap_b32_e32 v96, v100
	v_permlane16_swap_b32_e32 v97, v101
	v_permlane16_swap_b32_e32 v98, v102
	v_permlane16_swap_b32_e32 v99, v103
	v_permlane16_swap_b32_e32 v104, v108
	v_permlane16_swap_b32_e32 v105, v109
	v_permlane16_swap_b32_e32 v106, v110
	v_permlane16_swap_b32_e32 v107, v111
	v_permlane16_swap_b32_e32 v80, v84
	v_permlane16_swap_b32_e32 v81, v85
	v_permlane16_swap_b32_e32 v82, v86
	v_permlane16_swap_b32_e32 v83, v87
	v_permlane16_swap_b32_e32 v88, v92
	v_permlane16_swap_b32_e32 v89, v93
	v_permlane16_swap_b32_e32 v90, v94
	v_permlane16_swap_b32_e32 v91, v95
	v_permlane16_swap_b32_e32 v64, v68
	v_permlane16_swap_b32_e32 v65, v69
	v_permlane16_swap_b32_e32 v66, v70
	v_permlane16_swap_b32_e32 v67, v71
	v_permlane16_swap_b32_e32 v72, v76
	v_permlane16_swap_b32_e32 v73, v77
	v_permlane16_swap_b32_e32 v74, v78
	v_permlane16_swap_b32_e32 v75, v79
	v_permlane16_swap_b32_e32 v48, v52
	v_permlane16_swap_b32_e32 v49, v53
	v_permlane16_swap_b32_e32 v50, v54
	v_permlane16_swap_b32_e32 v51, v55
	v_permlane16_swap_b32_e32 v56, v60
	v_permlane16_swap_b32_e32 v57, v61
	v_permlane16_swap_b32_e32 v58, v62
	v_permlane16_swap_b32_e32 v59, v63
	v_permlane16_swap_b32_e32 v32, v36
	v_permlane16_swap_b32_e32 v33, v37
	v_permlane16_swap_b32_e32 v34, v38
	v_permlane16_swap_b32_e32 v35, v39
	v_permlane16_swap_b32_e32 v40, v44
	v_permlane16_swap_b32_e32 v41, v45
	v_permlane16_swap_b32_e32 v42, v46
	v_permlane16_swap_b32_e32 v43, v47
	v_permlane16_swap_b32_e32 v16, v20
	v_permlane16_swap_b32_e32 v17, v21
	v_permlane16_swap_b32_e32 v18, v22
	v_permlane16_swap_b32_e32 v19, v23
	v_permlane16_swap_b32_e32 v24, v28
	v_permlane16_swap_b32_e32 v25, v29
	v_permlane16_swap_b32_e32 v26, v30
	v_permlane16_swap_b32_e32 v27, v31
	v_permlane16_swap_b32_e32 v0, v4
	v_permlane16_swap_b32_e32 v1, v5
	v_permlane16_swap_b32_e32 v2, v6
	v_permlane16_swap_b32_e32 v3, v7
	v_permlane16_swap_b32_e32 v8, v12
	v_permlane16_swap_b32_e32 v9, v13
	v_permlane16_swap_b32_e32 v10, v14
	v_permlane16_swap_b32_e32 v11, v15
	v_permlane32_swap_b32_e32 v112, v116
	v_permlane32_swap_b32_e32 v113, v117
	v_permlane32_swap_b32_e32 v114, v118
	v_permlane32_swap_b32_e32 v115, v119
	v_permlane32_swap_b32_e32 v120, v124
	v_permlane32_swap_b32_e32 v121, v125
	v_permlane32_swap_b32_e32 v122, v126
	v_permlane32_swap_b32_e32 v123, v127
	v_permlane32_swap_b32_e32 v96, v100
	v_permlane32_swap_b32_e32 v97, v101
	v_permlane32_swap_b32_e32 v98, v102
	v_permlane32_swap_b32_e32 v99, v103
	v_permlane32_swap_b32_e32 v104, v108
	v_permlane32_swap_b32_e32 v105, v109
	v_permlane32_swap_b32_e32 v106, v110
	v_permlane32_swap_b32_e32 v107, v111
	v_permlane32_swap_b32_e32 v80, v84
	v_permlane32_swap_b32_e32 v81, v85
	v_permlane32_swap_b32_e32 v82, v86
	v_permlane32_swap_b32_e32 v83, v87
	v_permlane32_swap_b32_e32 v88, v92
	v_permlane32_swap_b32_e32 v89, v93
	v_permlane32_swap_b32_e32 v90, v94
	v_permlane32_swap_b32_e32 v91, v95
	v_permlane32_swap_b32_e32 v64, v68
	v_permlane32_swap_b32_e32 v65, v69
	v_permlane32_swap_b32_e32 v66, v70
	v_permlane32_swap_b32_e32 v67, v71
	v_permlane32_swap_b32_e32 v72, v76
	v_permlane32_swap_b32_e32 v73, v77
	v_permlane32_swap_b32_e32 v74, v78
	v_permlane32_swap_b32_e32 v75, v79
	v_permlane32_swap_b32_e32 v48, v52
	v_permlane32_swap_b32_e32 v49, v53
	v_permlane32_swap_b32_e32 v50, v54
	v_permlane32_swap_b32_e32 v51, v55
	v_permlane32_swap_b32_e32 v56, v60
	v_permlane32_swap_b32_e32 v57, v61
	v_permlane32_swap_b32_e32 v58, v62
	v_permlane32_swap_b32_e32 v59, v63
	v_permlane32_swap_b32_e32 v32, v36
	v_permlane32_swap_b32_e32 v33, v37
	v_permlane32_swap_b32_e32 v34, v38
	v_permlane32_swap_b32_e32 v35, v39
	v_permlane32_swap_b32_e32 v40, v44
	v_permlane32_swap_b32_e32 v41, v45
	v_permlane32_swap_b32_e32 v42, v46
	v_permlane32_swap_b32_e32 v43, v47
	v_permlane32_swap_b32_e32 v16, v20
	v_permlane32_swap_b32_e32 v17, v21
	v_permlane32_swap_b32_e32 v18, v22
	v_permlane32_swap_b32_e32 v19, v23
	v_permlane32_swap_b32_e32 v24, v28
	v_permlane32_swap_b32_e32 v25, v29
	v_permlane32_swap_b32_e32 v26, v30
	v_permlane32_swap_b32_e32 v27, v31
	v_permlane32_swap_b32_e32 v0, v4
	v_permlane32_swap_b32_e32 v1, v5
	v_permlane32_swap_b32_e32 v2, v6
	v_permlane32_swap_b32_e32 v3, v7
	v_permlane32_swap_b32_e32 v8, v12
	v_permlane32_swap_b32_e32 v9, v13
	v_permlane32_swap_b32_e32 v10, v14
	v_permlane32_swap_b32_e32 v11, v15
	s_nop 1
	s_branch .LBB0_163

.Lg163_loop:
	s_add_u32 s51, s50, 0x10000
	s_sub_u32 s53, s51, 0x28000
	s_cmp_ge_u32 s51, 0x28000
	s_cselect_b32 s51, s53, s51
	s_add_u32 s52, s49, 0x20000
	s_sub_u32 s53, s52, 0x28000
	s_cmp_ge_u32 s52, 0x28000
	s_cselect_b32 s52, s53, s52
	v_add_u32_e32 v246, s50, v244
	s_waitcnt lgkmcnt(4)
	s_waitcnt lgkmcnt(3)
	v_mfma_f32_16x16x32_bf16 v[112:115], v[192:195], v[224:227], v[112:115]
	v_mfma_f32_16x16x32_bf16 v[120:123], v[196:199], v[224:227], v[120:123]
	v_mfma_f32_16x16x32_bf16 v[96:99], v[200:203], v[224:227], v[96:99]
	v_mfma_f32_16x16x32_bf16 v[104:107], v[204:207], v[224:227], v[104:107]
	s_add_u32 m0, s51, s48
	s_nop 0
	global_load_lds_dwordx4 v248, s[64:65]
	s_add_u32 s64, s64, 0x80
	s_addc_u32 s65, s65, 0
	s_add_u32 s53, s51, s48
	s_add_u32 m0, s53, 0x2000
	s_nop 0
	global_load_lds_dwordx4 v248, s[66:67]
	s_add_u32 s66, s66, 0x80
	s_addc_u32 s67, s67, 0
	ds_read_b128 v[224:227], v245 offset:8192
	ds_read_b128 v[208:211], v246
	s_waitcnt lgkmcnt(4)
	v_mfma_f32_16x16x32_bf16 v[116:119], v[192:195], v[228:231], v[116:119]
	v_mfma_f32_16x16x32_bf16 v[124:127], v[196:199], v[228:231], v[124:127]
	v_mfma_f32_16x16x32_bf16 v[100:103], v[200:203], v[228:231], v[100:103]
	v_mfma_f32_16x16x32_bf16 v[108:111], v[204:207], v[228:231], v[108:111]
	s_add_u32 s53, s51, s48
	s_add_u32 m0, s53, 0x4000
	s_nop 0
	global_load_lds_dwordx4 v248, s[68:69]
	s_add_u32 s68, s68, 0x80
	s_addc_u32 s69, s69, 0
	s_add_u32 s53, s51, s48
	s_add_u32 m0, s53, 0x6000
	s_nop 0
	global_load_lds_dwordx4 v248, s[70:71]
	s_add_u32 s70, s70, 0x80
	s_addc_u32 s71, s71, 0
	ds_read_b128 v[228:231], v245 offset:10240
	ds_read_b128 v[212:215], v246 offset:2048
	s_waitcnt lgkmcnt(5)
	v_mfma_f32_16x16x32_bf16 v[80:83], v[192:195], v[232:235], v[80:83]
	v_mfma_f32_16x16x32_bf16 v[88:91], v[196:199], v[232:235], v[88:91]
	v_mfma_f32_16x16x32_bf16 v[64:67], v[200:203], v[232:235], v[64:67]
	v_mfma_f32_16x16x32_bf16 v[72:75], v[204:207], v[232:235], v[72:75]
	ds_read_b128 v[232:235], v245 offset:12288
	ds_read_b128 v[216:219], v246 offset:4096
	s_waitcnt lgkmcnt(6)
	v_mfma_f32_16x16x32_bf16 v[84:87], v[192:195], v[236:239], v[84:87]
	v_mfma_f32_16x16x32_bf16 v[92:95], v[196:199], v[236:239], v[92:95]
	v_mfma_f32_16x16x32_bf16 v[68:71], v[200:203], v[236:239], v[68:71]
	v_mfma_f32_16x16x32_bf16 v[76:79], v[204:207], v[236:239], v[76:79]
	ds_read_b128 v[236:239], v245 offset:14336
	ds_read_b128 v[220:223], v246 offset:6144
	v_add_u32_e32 v245, s49, v241
	s_waitcnt lgkmcnt(7)
	v_mfma_f32_16x16x32_bf16 v[48:51], v[192:195], v[224:227], v[48:51]
	v_mfma_f32_16x16x32_bf16 v[56:59], v[196:199], v[224:227], v[56:59]
	v_mfma_f32_16x16x32_bf16 v[32:35], v[200:203], v[224:227], v[32:35]
	v_mfma_f32_16x16x32_bf16 v[40:43], v[204:207], v[224:227], v[40:43]
	ds_read_b128 v[224:227], v245
	s_waitcnt lgkmcnt(6)
	v_mfma_f32_16x16x32_bf16 v[52:55], v[192:195], v[228:231], v[52:55]
	v_mfma_f32_16x16x32_bf16 v[60:63], v[196:199], v[228:231], v[60:63]
	v_mfma_f32_16x16x32_bf16 v[36:39], v[200:203], v[228:231], v[36:39]
	v_mfma_f32_16x16x32_bf16 v[44:47], v[204:207], v[228:231], v[44:47]
	ds_read_b128 v[228:231], v245 offset:2048
	s_waitcnt lgkmcnt(5)
	v_mfma_f32_16x16x32_bf16 v[16:19], v[192:195], v[232:235], v[16:19]
	v_mfma_f32_16x16x32_bf16 v[24:27], v[196:199], v[232:235], v[24:27]
	v_mfma_f32_16x16x32_bf16 v[0:3], v[200:203], v[232:235], v[0:3]
	v_mfma_f32_16x16x32_bf16 v[8:11], v[204:207], v[232:235], v[8:11]
	ds_read_b128 v[232:235], v245 offset:4096
	s_waitcnt lgkmcnt(4)
	v_mfma_f32_16x16x32_bf16 v[20:23], v[192:195], v[236:239], v[20:23]
	v_mfma_f32_16x16x32_bf16 v[28:31], v[196:199], v[236:239], v[28:31]
	v_mfma_f32_16x16x32_bf16 v[4:7], v[200:203], v[236:239], v[4:7]
	v_mfma_f32_16x16x32_bf16 v[12:15], v[204:207], v[236:239], v[12:15]
	ds_read_b128 v[236:239], v245 offset:6144
	s_waitcnt lgkmcnt(4)
	s_waitcnt lgkmcnt(3)
	v_mfma_f32_16x16x32_bf16 v[112:115], v[208:211], v[224:227], v[112:115]
	v_mfma_f32_16x16x32_bf16 v[120:123], v[212:215], v[224:227], v[120:123]
	v_mfma_f32_16x16x32_bf16 v[96:99], v[216:219], v[224:227], v[96:99]
	v_mfma_f32_16x16x32_bf16 v[104:107], v[220:223], v[224:227], v[104:107]
	ds_read_b128 v[224:227], v245 offset:8192
	s_waitcnt lgkmcnt(3)
	v_mfma_f32_16x16x32_bf16 v[116:119], v[208:211], v[228:231], v[116:119]
	v_mfma_f32_16x16x32_bf16 v[124:127], v[212:215], v[228:231], v[124:127]
	v_mfma_f32_16x16x32_bf16 v[100:103], v[216:219], v[228:231], v[100:103]
	v_mfma_f32_16x16x32_bf16 v[108:111], v[220:223], v[228:231], v[108:111]
	ds_read_b128 v[228:231], v245 offset:10240
	s_waitcnt lgkmcnt(3)
	v_mfma_f32_16x16x32_bf16 v[80:83], v[208:211], v[232:235], v[80:83]
	v_mfma_f32_16x16x32_bf16 v[88:91], v[212:215], v[232:235], v[88:91]
	v_mfma_f32_16x16x32_bf16 v[64:67], v[216:219], v[232:235], v[64:67]
	v_mfma_f32_16x16x32_bf16 v[72:75], v[220:223], v[232:235], v[72:75]
	ds_read_b128 v[232:235], v245 offset:12288
	s_waitcnt lgkmcnt(3)
	v_mfma_f32_16x16x32_bf16 v[84:87], v[208:211], v[236:239], v[84:87]
	v_mfma_f32_16x16x32_bf16 v[92:95], v[212:215], v[236:239], v[92:95]
	v_mfma_f32_16x16x32_bf16 v[68:71], v[216:219], v[236:239], v[68:71]
	v_mfma_f32_16x16x32_bf16 v[76:79], v[220:223], v[236:239], v[76:79]
	ds_read_b128 v[236:239], v245 offset:14336
	s_waitcnt lgkmcnt(3)
	v_mfma_f32_16x16x32_bf16 v[48:51], v[208:211], v[224:227], v[48:51]
	v_mfma_f32_16x16x32_bf16 v[56:59], v[212:215], v[224:227], v[56:59]
	v_mfma_f32_16x16x32_bf16 v[32:35], v[216:219], v[224:227], v[32:35]
	v_mfma_f32_16x16x32_bf16 v[40:43], v[220:223], v[224:227], v[40:43]
	s_add_u32 m0, s52, s48
	s_nop 0
	global_load_lds_dwordx4 v247, s[56:57]
	s_add_u32 s56, s56, 0x80
	s_addc_u32 s57, s57, 0
	s_add_u32 s53, s52, s48
	s_add_u32 m0, s53, 0x2000
	s_nop 0
	global_load_lds_dwordx4 v247, s[58:59]
	s_add_u32 s58, s58, 0x80
	s_addc_u32 s59, s59, 0
	s_waitcnt lgkmcnt(2)
	v_mfma_f32_16x16x32_bf16 v[52:55], v[208:211], v[228:231], v[52:55]
	v_mfma_f32_16x16x32_bf16 v[60:63], v[212:215], v[228:231], v[60:63]
	v_mfma_f32_16x16x32_bf16 v[36:39], v[216:219], v[228:231], v[36:39]
	v_mfma_f32_16x16x32_bf16 v[44:47], v[220:223], v[228:231], v[44:47]
	s_add_u32 s53, s52, s48
	s_add_u32 m0, s53, 0x4000
	s_nop 0
	global_load_lds_dwordx4 v247, s[60:61]
	s_add_u32 s60, s60, 0x80
	s_addc_u32 s61, s61, 0
	s_add_u32 s53, s52, s48
	s_add_u32 m0, s53, 0x6000
	s_nop 0
	global_load_lds_dwordx4 v247, s[62:63]
	s_add_u32 s62, s62, 0x80
	s_addc_u32 s63, s63, 0
	s_waitcnt lgkmcnt(1)
	v_mfma_f32_16x16x32_bf16 v[16:19], v[208:211], v[232:235], v[16:19]
	v_mfma_f32_16x16x32_bf16 v[24:27], v[212:215], v[232:235], v[24:27]
	v_mfma_f32_16x16x32_bf16 v[0:3], v[216:219], v[232:235], v[0:3]
	v_mfma_f32_16x16x32_bf16 v[8:11], v[220:223], v[232:235], v[8:11]
	s_waitcnt lgkmcnt(0)
	v_mfma_f32_16x16x32_bf16 v[20:23], v[208:211], v[236:239], v[20:23]
	v_mfma_f32_16x16x32_bf16 v[28:31], v[212:215], v[236:239], v[28:31]
	v_mfma_f32_16x16x32_bf16 v[4:7], v[216:219], v[236:239], v[4:7]
	v_mfma_f32_16x16x32_bf16 v[12:15], v[220:223], v[236:239], v[12:15]
	s_waitcnt lgkmcnt(0)
	s_add_u32 s28, s28, 0x80
	s_addc_u32 s29, s29, 0
	s_add_u32 s49, s49, 0x10000
	s_sub_u32 s53, s49, 0x28000
	s_cmp_ge_u32 s49, 0x28000
	s_cselect_b32 s49, s53, s49
	s_mov_b32 s50, s51
	s_waitcnt vmcnt(4)
	s_barrier
	v_add_u32_e32 v246, s50, v243
	v_add_u32_e32 v245, s49, v240
	ds_read_b128 v[192:195], v246
	ds_read_b128 v[196:199], v246 offset:2048
	ds_read_b128 v[200:203], v246 offset:4096
	ds_read_b128 v[204:207], v246 offset:6144
	ds_read_b128 v[224:227], v245
	ds_read_b128 v[228:231], v245 offset:2048
	ds_read_b128 v[232:235], v245 offset:4096
	ds_read_b128 v[236:239], v245 offset:6144
	s_cmpk_lg_i32 s28, 0xf00
	s_cbranch_scc1 .Lg163_loop
	s_add_u32 s51, s50, 0x10000
	s_sub_u32 s53, s51, 0x28000
	s_cmp_ge_u32 s51, 0x28000
	s_cselect_b32 s51, s53, s51
	v_add_u32_e32 v246, s50, v244
	s_waitcnt lgkmcnt(4)
	s_waitcnt lgkmcnt(3)
	v_mfma_f32_16x16x32_bf16 v[112:115], v[192:195], v[224:227], v[112:115]
	v_mfma_f32_16x16x32_bf16 v[120:123], v[196:199], v[224:227], v[120:123]
	v_mfma_f32_16x16x32_bf16 v[96:99], v[200:203], v[224:227], v[96:99]
	v_mfma_f32_16x16x32_bf16 v[104:107], v[204:207], v[224:227], v[104:107]
	s_add_u32 m0, s51, s48
	s_nop 0
	global_load_lds_dwordx4 v248, s[64:65]
	s_add_u32 s64, s64, 0x80
	s_addc_u32 s65, s65, 0
	s_add_u32 s53, s51, s48
	s_add_u32 m0, s53, 0x2000
	s_nop 0
	global_load_lds_dwordx4 v248, s[66:67]
	s_add_u32 s66, s66, 0x80
	s_addc_u32 s67, s67, 0
	ds_read_b128 v[224:227], v245 offset:8192
	ds_read_b128 v[208:211], v246
	s_waitcnt lgkmcnt(4)
	v_mfma_f32_16x16x32_bf16 v[116:119], v[192:195], v[228:231], v[116:119]
	v_mfma_f32_16x16x32_bf16 v[124:127], v[196:199], v[228:231], v[124:127]
	v_mfma_f32_16x16x32_bf16 v[100:103], v[200:203], v[228:231], v[100:103]
	v_mfma_f32_16x16x32_bf16 v[108:111], v[204:207], v[228:231], v[108:111]
	s_add_u32 s53, s51, s48
	s_add_u32 m0, s53, 0x4000
	s_nop 0
	global_load_lds_dwordx4 v248, s[68:69]
	s_add_u32 s68, s68, 0x80
	s_addc_u32 s69, s69, 0
	s_add_u32 s53, s51, s48
	s_add_u32 m0, s53, 0x6000
	s_nop 0
	global_load_lds_dwordx4 v248, s[70:71]
	s_add_u32 s70, s70, 0x80
	s_addc_u32 s71, s71, 0
	ds_read_b128 v[228:231], v245 offset:10240
	ds_read_b128 v[212:215], v246 offset:2048
	s_waitcnt lgkmcnt(5)
	v_mfma_f32_16x16x32_bf16 v[80:83], v[192:195], v[232:235], v[80:83]
	v_mfma_f32_16x16x32_bf16 v[88:91], v[196:199], v[232:235], v[88:91]
	v_mfma_f32_16x16x32_bf16 v[64:67], v[200:203], v[232:235], v[64:67]
	v_mfma_f32_16x16x32_bf16 v[72:75], v[204:207], v[232:235], v[72:75]
	ds_read_b128 v[232:235], v245 offset:12288
	ds_read_b128 v[216:219], v246 offset:4096
	s_waitcnt lgkmcnt(6)
	v_mfma_f32_16x16x32_bf16 v[84:87], v[192:195], v[236:239], v[84:87]
	v_mfma_f32_16x16x32_bf16 v[92:95], v[196:199], v[236:239], v[92:95]
	v_mfma_f32_16x16x32_bf16 v[68:71], v[200:203], v[236:239], v[68:71]
	v_mfma_f32_16x16x32_bf16 v[76:79], v[204:207], v[236:239], v[76:79]
	ds_read_b128 v[236:239], v245 offset:14336
	ds_read_b128 v[220:223], v246 offset:6144
	v_add_u32_e32 v245, s49, v241
	s_waitcnt lgkmcnt(7)
	v_mfma_f32_16x16x32_bf16 v[48:51], v[192:195], v[224:227], v[48:51]
	v_mfma_f32_16x16x32_bf16 v[56:59], v[196:199], v[224:227], v[56:59]
	v_mfma_f32_16x16x32_bf16 v[32:35], v[200:203], v[224:227], v[32:35]
	v_mfma_f32_16x16x32_bf16 v[40:43], v[204:207], v[224:227], v[40:43]
	ds_read_b128 v[224:227], v245
	s_waitcnt lgkmcnt(6)
	v_mfma_f32_16x16x32_bf16 v[52:55], v[192:195], v[228:231], v[52:55]
	v_mfma_f32_16x16x32_bf16 v[60:63], v[196:199], v[228:231], v[60:63]
	v_mfma_f32_16x16x32_bf16 v[36:39], v[200:203], v[228:231], v[36:39]
	v_mfma_f32_16x16x32_bf16 v[44:47], v[204:207], v[228:231], v[44:47]
	ds_read_b128 v[228:231], v245 offset:2048
	s_waitcnt lgkmcnt(5)
	v_mfma_f32_16x16x32_bf16 v[16:19], v[192:195], v[232:235], v[16:19]
	v_mfma_f32_16x16x32_bf16 v[24:27], v[196:199], v[232:235], v[24:27]
	v_mfma_f32_16x16x32_bf16 v[0:3], v[200:203], v[232:235], v[0:3]
	v_mfma_f32_16x16x32_bf16 v[8:11], v[204:207], v[232:235], v[8:11]
	ds_read_b128 v[232:235], v245 offset:4096
	s_waitcnt lgkmcnt(4)
	v_mfma_f32_16x16x32_bf16 v[20:23], v[192:195], v[236:239], v[20:23]
	v_mfma_f32_16x16x32_bf16 v[28:31], v[196:199], v[236:239], v[28:31]
	v_mfma_f32_16x16x32_bf16 v[4:7], v[200:203], v[236:239], v[4:7]
	v_mfma_f32_16x16x32_bf16 v[12:15], v[204:207], v[236:239], v[12:15]
	ds_read_b128 v[236:239], v245 offset:6144
	s_waitcnt lgkmcnt(4)
	s_waitcnt lgkmcnt(3)
	v_mfma_f32_16x16x32_bf16 v[112:115], v[208:211], v[224:227], v[112:115]
	v_mfma_f32_16x16x32_bf16 v[120:123], v[212:215], v[224:227], v[120:123]
	v_mfma_f32_16x16x32_bf16 v[96:99], v[216:219], v[224:227], v[96:99]
	v_mfma_f32_16x16x32_bf16 v[104:107], v[220:223], v[224:227], v[104:107]
	ds_read_b128 v[224:227], v245 offset:8192
	s_waitcnt lgkmcnt(3)
	v_mfma_f32_16x16x32_bf16 v[116:119], v[208:211], v[228:231], v[116:119]
	v_mfma_f32_16x16x32_bf16 v[124:127], v[212:215], v[228:231], v[124:127]
	v_mfma_f32_16x16x32_bf16 v[100:103], v[216:219], v[228:231], v[100:103]
	v_mfma_f32_16x16x32_bf16 v[108:111], v[220:223], v[228:231], v[108:111]
	ds_read_b128 v[228:231], v245 offset:10240
	s_waitcnt lgkmcnt(3)
	v_mfma_f32_16x16x32_bf16 v[80:83], v[208:211], v[232:235], v[80:83]
	v_mfma_f32_16x16x32_bf16 v[88:91], v[212:215], v[232:235], v[88:91]
	v_mfma_f32_16x16x32_bf16 v[64:67], v[216:219], v[232:235], v[64:67]
	v_mfma_f32_16x16x32_bf16 v[72:75], v[220:223], v[232:235], v[72:75]
	ds_read_b128 v[232:235], v245 offset:12288
	s_waitcnt lgkmcnt(3)
	v_mfma_f32_16x16x32_bf16 v[84:87], v[208:211], v[236:239], v[84:87]
	v_mfma_f32_16x16x32_bf16 v[92:95], v[212:215], v[236:239], v[92:95]
	v_mfma_f32_16x16x32_bf16 v[68:71], v[216:219], v[236:239], v[68:71]
	v_mfma_f32_16x16x32_bf16 v[76:79], v[220:223], v[236:239], v[76:79]
	ds_read_b128 v[236:239], v245 offset:14336
	s_waitcnt lgkmcnt(3)
	v_mfma_f32_16x16x32_bf16 v[48:51], v[208:211], v[224:227], v[48:51]
	v_mfma_f32_16x16x32_bf16 v[56:59], v[212:215], v[224:227], v[56:59]
	v_mfma_f32_16x16x32_bf16 v[32:35], v[216:219], v[224:227], v[32:35]
	v_mfma_f32_16x16x32_bf16 v[40:43], v[220:223], v[224:227], v[40:43]
	s_waitcnt lgkmcnt(2)
	v_mfma_f32_16x16x32_bf16 v[52:55], v[208:211], v[228:231], v[52:55]
	v_mfma_f32_16x16x32_bf16 v[60:63], v[212:215], v[228:231], v[60:63]
	v_mfma_f32_16x16x32_bf16 v[36:39], v[216:219], v[228:231], v[36:39]
	v_mfma_f32_16x16x32_bf16 v[44:47], v[220:223], v[228:231], v[44:47]
	s_waitcnt lgkmcnt(1)
	v_mfma_f32_16x16x32_bf16 v[16:19], v[208:211], v[232:235], v[16:19]
	v_mfma_f32_16x16x32_bf16 v[24:27], v[212:215], v[232:235], v[24:27]
	v_mfma_f32_16x16x32_bf16 v[0:3], v[216:219], v[232:235], v[0:3]
	v_mfma_f32_16x16x32_bf16 v[8:11], v[220:223], v[232:235], v[8:11]
	s_waitcnt lgkmcnt(0)
	v_mfma_f32_16x16x32_bf16 v[20:23], v[208:211], v[236:239], v[20:23]
	v_mfma_f32_16x16x32_bf16 v[28:31], v[212:215], v[236:239], v[28:31]
	v_mfma_f32_16x16x32_bf16 v[4:7], v[216:219], v[236:239], v[4:7]
	v_mfma_f32_16x16x32_bf16 v[12:15], v[220:223], v[236:239], v[12:15]
	s_waitcnt lgkmcnt(0)
	s_add_u32 s28, s28, 0x80
	s_addc_u32 s29, s29, 0
	s_add_u32 s49, s49, 0x10000
	s_sub_u32 s53, s49, 0x28000
	s_cmp_ge_u32 s49, 0x28000
	s_cselect_b32 s49, s53, s49
	s_mov_b32 s50, s51
	s_waitcnt vmcnt(0)
	s_barrier
	v_add_u32_e32 v246, s50, v243
	v_add_u32_e32 v245, s49, v240
	ds_read_b128 v[192:195], v246
	ds_read_b128 v[196:199], v246 offset:2048
	ds_read_b128 v[200:203], v246 offset:4096
	ds_read_b128 v[204:207], v246 offset:6144
	ds_read_b128 v[224:227], v245
	ds_read_b128 v[228:231], v245 offset:2048
	ds_read_b128 v[232:235], v245 offset:4096
	ds_read_b128 v[236:239], v245 offset:6144
	v_add_u32_e32 v246, s50, v244
	s_waitcnt lgkmcnt(4)
	s_waitcnt lgkmcnt(3)
	v_mfma_f32_16x16x32_bf16 v[112:115], v[192:195], v[224:227], v[112:115]
	v_mfma_f32_16x16x32_bf16 v[120:123], v[196:199], v[224:227], v[120:123]
	v_mfma_f32_16x16x32_bf16 v[96:99], v[200:203], v[224:227], v[96:99]
	v_mfma_f32_16x16x32_bf16 v[104:107], v[204:207], v[224:227], v[104:107]
	ds_read_b128 v[224:227], v245 offset:8192
	ds_read_b128 v[208:211], v246
	s_waitcnt lgkmcnt(4)
	v_mfma_f32_16x16x32_bf16 v[116:119], v[192:195], v[228:231], v[116:119]
	v_mfma_f32_16x16x32_bf16 v[124:127], v[196:199], v[228:231], v[124:127]
	v_mfma_f32_16x16x32_bf16 v[100:103], v[200:203], v[228:231], v[100:103]
	v_mfma_f32_16x16x32_bf16 v[108:111], v[204:207], v[228:231], v[108:111]
	ds_read_b128 v[228:231], v245 offset:10240
	ds_read_b128 v[212:215], v246 offset:2048
	s_waitcnt lgkmcnt(5)
	v_mfma_f32_16x16x32_bf16 v[80:83], v[192:195], v[232:235], v[80:83]
	v_mfma_f32_16x16x32_bf16 v[88:91], v[196:199], v[232:235], v[88:91]
	v_mfma_f32_16x16x32_bf16 v[64:67], v[200:203], v[232:235], v[64:67]
	v_mfma_f32_16x16x32_bf16 v[72:75], v[204:207], v[232:235], v[72:75]
	ds_read_b128 v[232:235], v245 offset:12288
	ds_read_b128 v[216:219], v246 offset:4096
	s_waitcnt lgkmcnt(6)
	v_mfma_f32_16x16x32_bf16 v[84:87], v[192:195], v[236:239], v[84:87]
	v_mfma_f32_16x16x32_bf16 v[92:95], v[196:199], v[236:239], v[92:95]
	v_mfma_f32_16x16x32_bf16 v[68:71], v[200:203], v[236:239], v[68:71]
	v_mfma_f32_16x16x32_bf16 v[76:79], v[204:207], v[236:239], v[76:79]
	ds_read_b128 v[236:239], v245 offset:14336
	ds_read_b128 v[220:223], v246 offset:6144
	v_add_u32_e32 v245, s49, v241
	s_waitcnt lgkmcnt(7)
	v_mfma_f32_16x16x32_bf16 v[48:51], v[192:195], v[224:227], v[48:51]
	v_mfma_f32_16x16x32_bf16 v[56:59], v[196:199], v[224:227], v[56:59]
	v_mfma_f32_16x16x32_bf16 v[32:35], v[200:203], v[224:227], v[32:35]
	v_mfma_f32_16x16x32_bf16 v[40:43], v[204:207], v[224:227], v[40:43]
	ds_read_b128 v[224:227], v245
	s_waitcnt lgkmcnt(6)
	v_mfma_f32_16x16x32_bf16 v[52:55], v[192:195], v[228:231], v[52:55]
	v_mfma_f32_16x16x32_bf16 v[60:63], v[196:199], v[228:231], v[60:63]
	v_mfma_f32_16x16x32_bf16 v[36:39], v[200:203], v[228:231], v[36:39]
	v_mfma_f32_16x16x32_bf16 v[44:47], v[204:207], v[228:231], v[44:47]
	ds_read_b128 v[228:231], v245 offset:2048
	s_waitcnt lgkmcnt(5)
	v_mfma_f32_16x16x32_bf16 v[16:19], v[192:195], v[232:235], v[16:19]
	v_mfma_f32_16x16x32_bf16 v[24:27], v[196:199], v[232:235], v[24:27]
	v_mfma_f32_16x16x32_bf16 v[0:3], v[200:203], v[232:235], v[0:3]
	v_mfma_f32_16x16x32_bf16 v[8:11], v[204:207], v[232:235], v[8:11]
	ds_read_b128 v[232:235], v245 offset:4096
	s_waitcnt lgkmcnt(4)
	v_mfma_f32_16x16x32_bf16 v[20:23], v[192:195], v[236:239], v[20:23]
	v_mfma_f32_16x16x32_bf16 v[28:31], v[196:199], v[236:239], v[28:31]
	v_mfma_f32_16x16x32_bf16 v[4:7], v[200:203], v[236:239], v[4:7]
	v_mfma_f32_16x16x32_bf16 v[12:15], v[204:207], v[236:239], v[12:15]
	ds_read_b128 v[236:239], v245 offset:6144
	s_waitcnt lgkmcnt(4)
	s_waitcnt lgkmcnt(3)
	v_mfma_f32_16x16x32_bf16 v[112:115], v[208:211], v[224:227], v[112:115]
	v_mfma_f32_16x16x32_bf16 v[120:123], v[212:215], v[224:227], v[120:123]
	v_mfma_f32_16x16x32_bf16 v[96:99], v[216:219], v[224:227], v[96:99]
	v_mfma_f32_16x16x32_bf16 v[104:107], v[220:223], v[224:227], v[104:107]
	ds_read_b128 v[224:227], v245 offset:8192
	s_waitcnt lgkmcnt(3)
	v_mfma_f32_16x16x32_bf16 v[116:119], v[208:211], v[228:231], v[116:119]
	v_mfma_f32_16x16x32_bf16 v[124:127], v[212:215], v[228:231], v[124:127]
	v_mfma_f32_16x16x32_bf16 v[100:103], v[216:219], v[228:231], v[100:103]
	v_mfma_f32_16x16x32_bf16 v[108:111], v[220:223], v[228:231], v[108:111]
	ds_read_b128 v[228:231], v245 offset:10240
	s_waitcnt lgkmcnt(3)
	v_mfma_f32_16x16x32_bf16 v[80:83], v[208:211], v[232:235], v[80:83]
	v_mfma_f32_16x16x32_bf16 v[88:91], v[212:215], v[232:235], v[88:91]
	v_mfma_f32_16x16x32_bf16 v[64:67], v[216:219], v[232:235], v[64:67]
	v_mfma_f32_16x16x32_bf16 v[72:75], v[220:223], v[232:235], v[72:75]
	ds_read_b128 v[232:235], v245 offset:12288
	s_waitcnt lgkmcnt(3)
	v_mfma_f32_16x16x32_bf16 v[84:87], v[208:211], v[236:239], v[84:87]
	v_mfma_f32_16x16x32_bf16 v[92:95], v[212:215], v[236:239], v[92:95]
	v_mfma_f32_16x16x32_bf16 v[68:71], v[216:219], v[236:239], v[68:71]
	v_mfma_f32_16x16x32_bf16 v[76:79], v[220:223], v[236:239], v[76:79]
	ds_read_b128 v[236:239], v245 offset:14336
	s_waitcnt lgkmcnt(3)
	v_mfma_f32_16x16x32_bf16 v[48:51], v[208:211], v[224:227], v[48:51]
	v_mfma_f32_16x16x32_bf16 v[56:59], v[212:215], v[224:227], v[56:59]
	v_mfma_f32_16x16x32_bf16 v[32:35], v[216:219], v[224:227], v[32:35]
	v_mfma_f32_16x16x32_bf16 v[40:43], v[220:223], v[224:227], v[40:43]
	s_waitcnt lgkmcnt(2)
	v_mfma_f32_16x16x32_bf16 v[52:55], v[208:211], v[228:231], v[52:55]
	v_mfma_f32_16x16x32_bf16 v[60:63], v[212:215], v[228:231], v[60:63]
	v_mfma_f32_16x16x32_bf16 v[36:39], v[216:219], v[228:231], v[36:39]
	v_mfma_f32_16x16x32_bf16 v[44:47], v[220:223], v[228:231], v[44:47]
	s_waitcnt lgkmcnt(1)
	v_mfma_f32_16x16x32_bf16 v[16:19], v[208:211], v[232:235], v[16:19]
	v_mfma_f32_16x16x32_bf16 v[24:27], v[212:215], v[232:235], v[24:27]
	v_mfma_f32_16x16x32_bf16 v[0:3], v[216:219], v[232:235], v[0:3]
	v_mfma_f32_16x16x32_bf16 v[8:11], v[220:223], v[232:235], v[8:11]
	s_waitcnt lgkmcnt(0)
	v_mfma_f32_16x16x32_bf16 v[20:23], v[208:211], v[236:239], v[20:23]
	v_mfma_f32_16x16x32_bf16 v[28:31], v[212:215], v[236:239], v[28:31]
	v_mfma_f32_16x16x32_bf16 v[4:7], v[216:219], v[236:239], v[4:7]
	v_mfma_f32_16x16x32_bf16 v[12:15], v[220:223], v[236:239], v[12:15]
	s_waitcnt lgkmcnt(0)
	s_waitcnt vmcnt(0)
	s_barrier
	s_nop 15
	v_permlane16_swap_b32_e32 v112, v116
	v_permlane16_swap_b32_e32 v113, v117
	v_permlane16_swap_b32_e32 v114, v118
	v_permlane16_swap_b32_e32 v115, v119
	v_permlane16_swap_b32_e32 v120, v124
	v_permlane16_swap_b32_e32 v121, v125
	v_permlane16_swap_b32_e32 v122, v126
	v_permlane16_swap_b32_e32 v123, v127
	v_permlane16_swap_b32_e32 v96, v100
	v_permlane16_swap_b32_e32 v97, v101
	v_permlane16_swap_b32_e32 v98, v102
	v_permlane16_swap_b32_e32 v99, v103
	v_permlane16_swap_b32_e32 v104, v108
	v_permlane16_swap_b32_e32 v105, v109
	v_permlane16_swap_b32_e32 v106, v110
	v_permlane16_swap_b32_e32 v107, v111
	v_permlane16_swap_b32_e32 v80, v84
	v_permlane16_swap_b32_e32 v81, v85
	v_permlane16_swap_b32_e32 v82, v86
	v_permlane16_swap_b32_e32 v83, v87
	v_permlane16_swap_b32_e32 v88, v92
	v_permlane16_swap_b32_e32 v89, v93
	v_permlane16_swap_b32_e32 v90, v94
	v_permlane16_swap_b32_e32 v91, v95
	v_permlane16_swap_b32_e32 v64, v68
	v_permlane16_swap_b32_e32 v65, v69
	v_permlane16_swap_b32_e32 v66, v70
	v_permlane16_swap_b32_e32 v67, v71
	v_permlane16_swap_b32_e32 v72, v76
	v_permlane16_swap_b32_e32 v73, v77
	v_permlane16_swap_b32_e32 v74, v78
	v_permlane16_swap_b32_e32 v75, v79
	v_permlane16_swap_b32_e32 v48, v52
	v_permlane16_swap_b32_e32 v49, v53
	v_permlane16_swap_b32_e32 v50, v54
	v_permlane16_swap_b32_e32 v51, v55
	v_permlane16_swap_b32_e32 v56, v60
	v_permlane16_swap_b32_e32 v57, v61
	v_permlane16_swap_b32_e32 v58, v62
	v_permlane16_swap_b32_e32 v59, v63
	v_permlane16_swap_b32_e32 v32, v36
	v_permlane16_swap_b32_e32 v33, v37
	v_permlane16_swap_b32_e32 v34, v38
	v_permlane16_swap_b32_e32 v35, v39
	v_permlane16_swap_b32_e32 v40, v44
	v_permlane16_swap_b32_e32 v41, v45
	v_permlane16_swap_b32_e32 v42, v46
	v_permlane16_swap_b32_e32 v43, v47
	v_permlane16_swap_b32_e32 v16, v20
	v_permlane16_swap_b32_e32 v17, v21
	v_permlane16_swap_b32_e32 v18, v22
	v_permlane16_swap_b32_e32 v19, v23
	v_permlane16_swap_b32_e32 v24, v28
	v_permlane16_swap_b32_e32 v25, v29
	v_permlane16_swap_b32_e32 v26, v30
	v_permlane16_swap_b32_e32 v27, v31
	v_permlane16_swap_b32_e32 v0, v4
	v_permlane16_swap_b32_e32 v1, v5
	v_permlane16_swap_b32_e32 v2, v6
	v_permlane16_swap_b32_e32 v3, v7
	v_permlane16_swap_b32_e32 v8, v12
	v_permlane16_swap_b32_e32 v9, v13
	v_permlane16_swap_b32_e32 v10, v14
	v_permlane16_swap_b32_e32 v11, v15
	v_permlane32_swap_b32_e32 v112, v116
	v_permlane32_swap_b32_e32 v113, v117
	v_permlane32_swap_b32_e32 v114, v118
	v_permlane32_swap_b32_e32 v115, v119
	v_permlane32_swap_b32_e32 v120, v124
	v_permlane32_swap_b32_e32 v121, v125
	v_permlane32_swap_b32_e32 v122, v126
	v_permlane32_swap_b32_e32 v123, v127
	v_permlane32_swap_b32_e32 v96, v100
	v_permlane32_swap_b32_e32 v97, v101
	v_permlane32_swap_b32_e32 v98, v102
	v_permlane32_swap_b32_e32 v99, v103
	v_permlane32_swap_b32_e32 v104, v108
	v_permlane32_swap_b32_e32 v105, v109
	v_permlane32_swap_b32_e32 v106, v110
	v_permlane32_swap_b32_e32 v107, v111
	v_permlane32_swap_b32_e32 v80, v84
	v_permlane32_swap_b32_e32 v81, v85
	v_permlane32_swap_b32_e32 v82, v86
	v_permlane32_swap_b32_e32 v83, v87
	v_permlane32_swap_b32_e32 v88, v92
	v_permlane32_swap_b32_e32 v89, v93
	v_permlane32_swap_b32_e32 v90, v94
	v_permlane32_swap_b32_e32 v91, v95
	v_permlane32_swap_b32_e32 v64, v68
	v_permlane32_swap_b32_e32 v65, v69
	v_permlane32_swap_b32_e32 v66, v70
	v_permlane32_swap_b32_e32 v67, v71
	v_permlane32_swap_b32_e32 v72, v76
	v_permlane32_swap_b32_e32 v73, v77
	v_permlane32_swap_b32_e32 v74, v78
	v_permlane32_swap_b32_e32 v75, v79
	v_permlane32_swap_b32_e32 v48, v52
	v_permlane32_swap_b32_e32 v49, v53
	v_permlane32_swap_b32_e32 v50, v54
	v_permlane32_swap_b32_e32 v51, v55
	v_permlane32_swap_b32_e32 v56, v60
	v_permlane32_swap_b32_e32 v57, v61
	v_permlane32_swap_b32_e32 v58, v62
	v_permlane32_swap_b32_e32 v59, v63
	v_permlane32_swap_b32_e32 v32, v36
	v_permlane32_swap_b32_e32 v33, v37
	v_permlane32_swap_b32_e32 v34, v38
	v_permlane32_swap_b32_e32 v35, v39
	v_permlane32_swap_b32_e32 v40, v44
	v_permlane32_swap_b32_e32 v41, v45
	v_permlane32_swap_b32_e32 v42, v46
	v_permlane32_swap_b32_e32 v43, v47
	v_permlane32_swap_b32_e32 v16, v20
	v_permlane32_swap_b32_e32 v17, v21
	v_permlane32_swap_b32_e32 v18, v22
	v_permlane32_swap_b32_e32 v19, v23
	v_permlane32_swap_b32_e32 v24, v28
	v_permlane32_swap_b32_e32 v25, v29
	v_permlane32_swap_b32_e32 v26, v30
	v_permlane32_swap_b32_e32 v27, v31
	v_permlane32_swap_b32_e32 v0, v4
	v_permlane32_swap_b32_e32 v1, v5
	v_permlane32_swap_b32_e32 v2, v6
	v_permlane32_swap_b32_e32 v3, v7
	v_permlane32_swap_b32_e32 v8, v12
	v_permlane32_swap_b32_e32 v9, v13
	v_permlane32_swap_b32_e32 v10, v14
	v_permlane32_swap_b32_e32 v11, v15
	s_nop 1
